# v60 + K-loop back edge rotated: taken branch at the tail of phase 4's load segment (loop head = phase 4's MMA segment, exit path has its own copy)
# baseline (speedup 1.0000x reference)
; #define PG8_WAIT_V(n) asm volatile("s_waitcnt vmcnt(" #n ")" ::: "memory")
; template <class Epi, bool ALIGN_EPI, bool SP2, class Hook>
; __device__ __forceinline__ void gemm_phase(LAS unsigned char* lds, const Gemm g, const StaticOrder& S, const Epi& E, Acc& acc, const bool fresh, const Hook& H, const int wave_id) {
;     ...
;         for (int t = t0; t < nt; t += 2) {
;             const bool last = (t == nt - 2);
;             const Src a1 = cA + (size_t)(t + 1) * kstep;
;             const Src a2 = last ? nA : cA + (size_t)(t + 2) * kstep, b2 = last ? nB : cB + (size_t)(t + 2) * kstep;
;             const Src a3 = a2 + kstep, b3 = b2 + kstep;
;             if (last && has_next) H(nxt);
;             if constexpr (SP2) {
;             PG8_TRIP_SP2(PG8_WAIT_V(8));
.LBB0_390:
	s_add_i32 s29, s12, -2
	s_lshl_b32 s12, s12, 7
	s_add_i32 s14, s14, s12
	s_add_i32 s12, s13, s12
	s_add_i32 s56, s14, 0x40080
	s_add_i32 s57, s12, 0x100
	s_branch .Lrot_in_1
.LBB0_391:
	s_setprio 1
	s_barrier
	v_mfma_f32_16x16x32_bf16 v[72:75], v[132:135], v[174:177], v[72:75]
	v_mfma_f32_16x16x32_bf16 v[60:63], v[140:143], v[174:177], v[60:63]
	v_mfma_f32_16x16x32_bf16 v[40:43], v[132:135], v[182:185], v[40:43]
	v_mfma_f32_16x16x32_bf16 v[32:35], v[140:143], v[182:185], v[32:35]
	v_mfma_f32_16x16x32_bf16 v[16:19], v[132:135], v[190:193], v[16:19]
	v_mfma_f32_16x16x32_bf16 v[12:15], v[140:143], v[190:193], v[12:15]
	v_mfma_f32_16x16x32_bf16 v[6:9], v[132:135], v[216:219], v[8:11]
	v_mfma_f32_16x16x32_bf16 v[2:5], v[140:143], v[216:219], v[2:5]
	v_mfma_f32_16x16x32_bf16 v[72:75], v[136:139], v[178:181], v[72:75]
	v_mfma_f32_16x16x32_bf16 v[60:63], v[154:157], v[178:181], v[60:63]
	v_mfma_f32_16x16x32_bf16 v[40:43], v[136:139], v[186:189], v[40:43]
	v_mfma_f32_16x16x32_bf16 v[32:35], v[154:157], v[186:189], v[32:35]
	v_mfma_f32_16x16x32_bf16 v[16:19], v[136:139], v[212:215], v[16:19]
	v_mfma_f32_16x16x32_bf16 v[12:15], v[154:157], v[212:215], v[12:15]
	v_mfma_f32_16x16x32_bf16 v[8:11], v[136:139], v[228:231], v[6:9]
	v_mfma_f32_16x16x32_bf16 v[4:7], v[154:157], v[228:231], v[2:5]
	v_mfma_f32_16x16x32_bf16 v[96:99], v[158:161], v[174:177], v[96:99]
	v_mfma_f32_16x16x32_bf16 v[104:107], v[166:169], v[174:177], v[104:107]
	v_mfma_f32_16x16x32_bf16 v[84:87], v[158:161], v[182:185], v[84:87]
	v_mfma_f32_16x16x32_bf16 v[76:79], v[166:169], v[182:185], v[76:79]
	v_mfma_f32_16x16x32_bf16 v[52:55], v[158:161], v[190:193], v[52:55]
	v_mfma_f32_16x16x32_bf16 v[44:47], v[166:169], v[190:193], v[44:47]
	v_mfma_f32_16x16x32_bf16 v[24:27], v[158:161], v[216:219], v[24:27]
	v_mfma_f32_16x16x32_bf16 v[20:23], v[166:169], v[216:219], v[20:23]
	v_mfma_f32_16x16x32_bf16 v[96:99], v[162:165], v[178:181], v[96:99]
	v_mfma_f32_16x16x32_bf16 v[104:107], v[170:173], v[178:181], v[104:107]
	v_mfma_f32_16x16x32_bf16 v[84:87], v[162:165], v[186:189], v[84:87]
	v_mfma_f32_16x16x32_bf16 v[76:79], v[170:173], v[186:189], v[76:79]
	v_mfma_f32_16x16x32_bf16 v[52:55], v[162:165], v[212:215], v[52:55]
	v_mfma_f32_16x16x32_bf16 v[44:47], v[170:173], v[212:215], v[44:47]
	v_mfma_f32_16x16x32_bf16 v[24:27], v[162:165], v[228:231], v[24:27]
	v_mfma_f32_16x16x32_bf16 v[20:23], v[170:173], v[228:231], v[20:23]
	s_barrier
	s_setprio 0
.Lrot_in_1:
	s_add_i32 s100, s56, 0xfffc0000
	v_add_u32_e32 v150, 0x10000, v148
	v_add_u32_e32 v151, 0x14000, v148
	ds_read_b128 v[132:135], v150
	ds_read_b128 v[136:139], v150 offset:1024
	ds_read_b128 v[140:143], v150 offset:2048
	ds_read_b128 v[152:155], v150 offset:3072
	ds_read_b128 v[156:159], v151
	ds_read_b128 v[160:163], v151 offset:1024
	ds_read_b128 v[164:167], v151 offset:2048
	ds_read_b128 v[168:171], v151 offset:3072
	s_mov_b32 m0, s41
	s_nop 0
	buffer_load_dwordx4 v144, s[8:11], s100 offen lds
	s_mov_b32 m0, s33
	s_nop 0
	buffer_load_dwordx4 v146, s[8:11], s100 offen lds
	s_mov_b32 m0, s45
	ds_read_b128 v[172:175], v149
	ds_read_b128 v[176:179], v149 offset:1024
	ds_read_b128 v[180:183], v149 offset:2048
	ds_read_b128 v[184:187], v149 offset:3072
	ds_read_b128 v[188:191], v149 offset:4096
	ds_read_b128 v[212:215], v149 offset:5120
	ds_read_b128 v[216:219], v149 offset:6144
	ds_read_b128 v[228:231], v149 offset:7168
	buffer_load_dwordx4 v144, s[8:11], s56 offen lds
	s_mov_b32 m0, s46
	s_nop 0
	buffer_load_dwordx4 v146, s[8:11], s56 offen lds
	s_waitcnt vmcnt(8)
	s_waitcnt lgkmcnt(0)
	s_setprio 1
	s_barrier
	v_mfma_f32_16x16x32_bf16 v[120:123], v[132:135], v[172:175], v[120:123]
	v_mfma_f32_16x16x32_bf16 v[112:115], v[140:143], v[172:175], v[112:115]
	v_mfma_f32_16x16x32_bf16 v[100:103], v[132:135], v[180:183], v[100:103]
	v_mfma_f32_16x16x32_bf16 v[88:91], v[140:143], v[180:183], v[88:91]
	v_mfma_f32_16x16x32_bf16 v[68:71], v[132:135], v[188:191], v[68:71]
	v_mfma_f32_16x16x32_bf16 v[56:59], v[140:143], v[188:191], v[56:59]
	v_mfma_f32_16x16x32_bf16 v[36:39], v[132:135], v[216:219], v[36:39]
	v_mfma_f32_16x16x32_bf16 v[28:31], v[140:143], v[216:219], v[28:31]
	v_mfma_f32_16x16x32_bf16 v[120:123], v[136:139], v[176:179], v[120:123]
	v_mfma_f32_16x16x32_bf16 v[112:115], v[152:155], v[176:179], v[112:115]
	v_mfma_f32_16x16x32_bf16 v[100:103], v[136:139], v[184:187], v[100:103]
	v_mfma_f32_16x16x32_bf16 v[88:91], v[152:155], v[184:187], v[88:91]
	v_mfma_f32_16x16x32_bf16 v[68:71], v[136:139], v[212:215], v[68:71]
	v_mfma_f32_16x16x32_bf16 v[56:59], v[152:155], v[212:215], v[56:59]
	v_mfma_f32_16x16x32_bf16 v[36:39], v[136:139], v[228:231], v[36:39]
	v_mfma_f32_16x16x32_bf16 v[28:31], v[152:155], v[228:231], v[28:31]
	v_mfma_f32_16x16x32_bf16 v[128:131], v[156:159], v[172:175], v[128:131]
	v_mfma_f32_16x16x32_bf16 v[124:127], v[164:167], v[172:175], v[124:127]
	v_mfma_f32_16x16x32_bf16 v[116:119], v[156:159], v[180:183], v[116:119]
	v_mfma_f32_16x16x32_bf16 v[108:111], v[164:167], v[180:183], v[108:111]
	v_mfma_f32_16x16x32_bf16 v[92:95], v[156:159], v[188:191], v[92:95]
	v_mfma_f32_16x16x32_bf16 v[80:83], v[164:167], v[188:191], v[80:83]
	v_mfma_f32_16x16x32_bf16 v[64:67], v[156:159], v[216:219], v[64:67]
	v_mfma_f32_16x16x32_bf16 v[48:51], v[164:167], v[216:219], v[48:51]
	v_mfma_f32_16x16x32_bf16 v[128:131], v[160:163], v[176:179], v[128:131]
	v_mfma_f32_16x16x32_bf16 v[124:127], v[168:171], v[176:179], v[124:127]
	v_mfma_f32_16x16x32_bf16 v[116:119], v[160:163], v[184:187], v[116:119]
	v_mfma_f32_16x16x32_bf16 v[108:111], v[168:171], v[184:187], v[108:111]
	v_mfma_f32_16x16x32_bf16 v[92:95], v[160:163], v[212:215], v[92:95]
	v_mfma_f32_16x16x32_bf16 v[80:83], v[168:171], v[212:215], v[80:83]
	v_mfma_f32_16x16x32_bf16 v[64:67], v[160:163], v[228:231], v[64:67]
	v_mfma_f32_16x16x32_bf16 v[48:51], v[168:171], v[228:231], v[48:51]
	s_barrier
; template <class Epi, bool ALIGN_EPI, bool SP2, class Hook>
; __device__ __forceinline__ void gemm_phase(LAS unsigned char* lds, const Gemm g, const StaticOrder& S, const Epi& E, Acc& acc, const bool fresh, const Hook& H, const int wave_id) {
;     ...
;         for (int t = t0; t < nt; t += 2) {
;             const bool last = (t == nt - 2);
;             const Src a1 = cA + (size_t)(t + 1) * kstep;
;             const Src a2 = last ? nA : cA + (size_t)(t + 2) * kstep, b2 = last ? nB : cB + (size_t)(t + 2) * kstep;
;             const Src a3 = a2 + kstep, b3 = b2 + kstep;
	s_setprio 0
	s_add_i32 s12, s56, 0xfffc0080
	s_cmp_eq_u32 s29, 12
	s_cselect_b32 s60, s68, s12
	s_cselect_b32 s13, s5, s77
	s_cselect_b32 s12, s4, s76
	s_cselect_b32 s15, s7, s55
	s_cselect_b32 s14, s6, s54
	s_cselect_b32 s58, s69, s57
	s_cselect_b32 s16, s0, s8
	s_cselect_b32 s17, s1, s9
	s_cselect_b32 s18, s2, s10
	s_cselect_b32 s19, s3, s11
	s_or_b32 s59, s60, 0x80
	s_mov_b32 m0, s92
	ds_read_b128 v[172:175], v149 offset:16384
	ds_read_b128 v[176:179], v149 offset:17408
	ds_read_b128 v[180:183], v149 offset:18432
	ds_read_b128 v[184:187], v149 offset:19456
	ds_read_b128 v[188:191], v149 offset:20480
	ds_read_b128 v[212:215], v149 offset:21504
	ds_read_b128 v[216:219], v149 offset:22528
	ds_read_b128 v[228:231], v149 offset:23552
	buffer_load_dwordx4 v145, s[12:15], s58 offen lds
	s_mov_b32 m0, s93
	s_add_i32 s61, s58, 0x40000
	buffer_load_dwordx4 v147, s[12:15], s58 offen lds
	s_mov_b32 m0, s94
	s_nop 0
	buffer_load_dwordx4 v145, s[12:15], s61 offen lds
	s_mov_b32 m0, s95
	s_nop 0
	buffer_load_dwordx4 v147, s[12:15], s61 offen lds
	s_waitcnt vmcnt(6)
	s_waitcnt lgkmcnt(0)
	s_setprio 1
	s_barrier
	v_mfma_f32_16x16x32_bf16 v[72:75], v[132:135], v[172:175], v[72:75]
	v_mfma_f32_16x16x32_bf16 v[60:63], v[140:143], v[172:175], v[60:63]
	v_mfma_f32_16x16x32_bf16 v[40:43], v[132:135], v[180:183], v[40:43]
	v_mfma_f32_16x16x32_bf16 v[32:35], v[140:143], v[180:183], v[32:35]
	v_mfma_f32_16x16x32_bf16 v[16:19], v[132:135], v[188:191], v[16:19]
	v_mfma_f32_16x16x32_bf16 v[12:15], v[140:143], v[188:191], v[12:15]
	v_mfma_f32_16x16x32_bf16 v[8:11], v[132:135], v[216:219], v[8:11]
	v_mfma_f32_16x16x32_bf16 v[2:5], v[140:143], v[216:219], v[4:7]
	v_mfma_f32_16x16x32_bf16 v[72:75], v[136:139], v[176:179], v[72:75]
	v_mfma_f32_16x16x32_bf16 v[60:63], v[152:155], v[176:179], v[60:63]
	v_mfma_f32_16x16x32_bf16 v[40:43], v[136:139], v[184:187], v[40:43]
	v_mfma_f32_16x16x32_bf16 v[32:35], v[152:155], v[184:187], v[32:35]
	v_mfma_f32_16x16x32_bf16 v[16:19], v[136:139], v[212:215], v[16:19]
	v_mfma_f32_16x16x32_bf16 v[12:15], v[152:155], v[212:215], v[12:15]
	v_mfma_f32_16x16x32_bf16 v[8:11], v[136:139], v[228:231], v[8:11]
	v_mfma_f32_16x16x32_bf16 v[2:5], v[152:155], v[228:231], v[2:5]
	v_mfma_f32_16x16x32_bf16 v[96:99], v[156:159], v[172:175], v[96:99]
	v_mfma_f32_16x16x32_bf16 v[104:107], v[164:167], v[172:175], v[104:107]
	v_mfma_f32_16x16x32_bf16 v[84:87], v[156:159], v[180:183], v[84:87]
	v_mfma_f32_16x16x32_bf16 v[76:79], v[164:167], v[180:183], v[76:79]
	v_mfma_f32_16x16x32_bf16 v[52:55], v[156:159], v[188:191], v[52:55]
	v_mfma_f32_16x16x32_bf16 v[44:47], v[164:167], v[188:191], v[44:47]
	v_mfma_f32_16x16x32_bf16 v[24:27], v[156:159], v[216:219], v[24:27]
	v_mfma_f32_16x16x32_bf16 v[20:23], v[164:167], v[216:219], v[20:23]
	v_mfma_f32_16x16x32_bf16 v[96:99], v[160:163], v[176:179], v[96:99]
	v_mfma_f32_16x16x32_bf16 v[104:107], v[168:171], v[176:179], v[104:107]
	v_mfma_f32_16x16x32_bf16 v[84:87], v[160:163], v[184:187], v[84:87]
	v_mfma_f32_16x16x32_bf16 v[76:79], v[168:171], v[184:187], v[76:79]
	v_mfma_f32_16x16x32_bf16 v[52:55], v[160:163], v[212:215], v[52:55]
	v_mfma_f32_16x16x32_bf16 v[44:47], v[168:171], v[212:215], v[44:47]
	v_mfma_f32_16x16x32_bf16 v[24:27], v[160:163], v[228:231], v[24:27]
	v_mfma_f32_16x16x32_bf16 v[20:23], v[168:171], v[228:231], v[20:23]
	s_barrier
	s_setprio 0
	s_mov_b32 m0, s44
	s_nop 0
	buffer_load_dwordx4 v144, s[16:19], s60 offen lds
	s_mov_b32 m0, s36
	s_nop 0
	buffer_load_dwordx4 v146, s[16:19], s60 offen lds
	v_add_u32_e32 v152, 0x18000, v148
	v_add_u32_e32 v153, 0x1c000, v148
	ds_read_b128 v[132:135], v152
	ds_read_b128 v[136:139], v152 offset:1024
	ds_read_b128 v[140:143], v152 offset:2048
	ds_read_b128 v[154:157], v152 offset:3072
	ds_read_b128 v[158:161], v153
	ds_read_b128 v[162:165], v153 offset:1024
	ds_read_b128 v[166:169], v153 offset:2048
	ds_read_b128 v[170:173], v153 offset:3072
	s_add_i32 s60, s60, 0x40000
	s_mov_b32 m0, s37
	ds_read_b128 v[174:177], v149 offset:32768
	ds_read_b128 v[178:181], v149 offset:33792
	ds_read_b128 v[182:185], v149 offset:34816
	ds_read_b128 v[186:189], v149 offset:35840
	ds_read_b128 v[190:193], v149 offset:36864
	ds_read_b128 v[212:215], v149 offset:37888
	ds_read_b128 v[216:219], v149 offset:38912
	ds_read_b128 v[228:231], v149 offset:39936
	buffer_load_dwordx4 v144, s[16:19], s60 offen lds
	s_mov_b32 m0, s38
	s_nop 0
	buffer_load_dwordx4 v146, s[16:19], s60 offen lds
	s_waitcnt vmcnt(8)
	s_waitcnt lgkmcnt(0)
	s_setprio 1
	s_barrier
	v_mfma_f32_16x16x32_bf16 v[120:123], v[132:135], v[174:177], v[120:123]
	v_mfma_f32_16x16x32_bf16 v[112:115], v[140:143], v[174:177], v[112:115]
	v_mfma_f32_16x16x32_bf16 v[100:103], v[132:135], v[182:185], v[100:103]
	v_mfma_f32_16x16x32_bf16 v[88:91], v[140:143], v[182:185], v[88:91]
	v_mfma_f32_16x16x32_bf16 v[68:71], v[132:135], v[190:193], v[68:71]
	v_mfma_f32_16x16x32_bf16 v[56:59], v[140:143], v[190:193], v[56:59]
	v_mfma_f32_16x16x32_bf16 v[36:39], v[132:135], v[216:219], v[36:39]
	v_mfma_f32_16x16x32_bf16 v[28:31], v[140:143], v[216:219], v[28:31]
	v_mfma_f32_16x16x32_bf16 v[120:123], v[136:139], v[178:181], v[120:123]
	v_mfma_f32_16x16x32_bf16 v[112:115], v[154:157], v[178:181], v[112:115]
	v_mfma_f32_16x16x32_bf16 v[100:103], v[136:139], v[186:189], v[100:103]
	v_mfma_f32_16x16x32_bf16 v[88:91], v[154:157], v[186:189], v[88:91]
	v_mfma_f32_16x16x32_bf16 v[68:71], v[136:139], v[212:215], v[68:71]
	v_mfma_f32_16x16x32_bf16 v[56:59], v[154:157], v[212:215], v[56:59]
	v_mfma_f32_16x16x32_bf16 v[36:39], v[136:139], v[228:231], v[36:39]
	v_mfma_f32_16x16x32_bf16 v[28:31], v[154:157], v[228:231], v[28:31]
	v_mfma_f32_16x16x32_bf16 v[128:131], v[158:161], v[174:177], v[128:131]
	v_mfma_f32_16x16x32_bf16 v[124:127], v[166:169], v[174:177], v[124:127]
	v_mfma_f32_16x16x32_bf16 v[116:119], v[158:161], v[182:185], v[116:119]
	v_mfma_f32_16x16x32_bf16 v[108:111], v[166:169], v[182:185], v[108:111]
	v_mfma_f32_16x16x32_bf16 v[92:95], v[158:161], v[190:193], v[92:95]
	v_mfma_f32_16x16x32_bf16 v[80:83], v[166:169], v[190:193], v[80:83]
	v_mfma_f32_16x16x32_bf16 v[64:67], v[158:161], v[216:219], v[64:67]
	v_mfma_f32_16x16x32_bf16 v[48:51], v[166:169], v[216:219], v[48:51]
	v_mfma_f32_16x16x32_bf16 v[128:131], v[162:165], v[178:181], v[128:131]
	v_mfma_f32_16x16x32_bf16 v[124:127], v[170:173], v[178:181], v[124:127]
	v_mfma_f32_16x16x32_bf16 v[116:119], v[162:165], v[186:189], v[116:119]
	v_mfma_f32_16x16x32_bf16 v[108:111], v[170:173], v[186:189], v[108:111]
	v_mfma_f32_16x16x32_bf16 v[92:95], v[162:165], v[212:215], v[92:95]
	v_mfma_f32_16x16x32_bf16 v[80:83], v[170:173], v[212:215], v[80:83]
	v_mfma_f32_16x16x32_bf16 v[64:67], v[162:165], v[228:231], v[64:67]
	v_mfma_f32_16x16x32_bf16 v[48:51], v[170:173], v[228:231], v[48:51]
	s_barrier
	s_setprio 0
	s_mov_b32 m0, s39
	s_or_b32 s60, s58, 0x80
	ds_read_b128 v[174:177], v149 offset:49152
	ds_read_b128 v[178:181], v149 offset:50176
	ds_read_b128 v[182:185], v149 offset:51200
	ds_read_b128 v[186:189], v149 offset:52224
	ds_read_b128 v[190:193], v149 offset:53248
	ds_read_b128 v[212:215], v149 offset:54272
	ds_read_b128 v[216:219], v149 offset:55296
	ds_read_b128 v[228:231], v149 offset:56320
	buffer_load_dwordx4 v145, s[12:15], s60 offen lds
	s_mov_b32 m0, s40
	s_add_i32 s58, s58, 0x40080
	buffer_load_dwordx4 v147, s[12:15], s60 offen lds
	s_mov_b32 m0, s43
	s_nop 0
	buffer_load_dwordx4 v145, s[12:15], s58 offen lds
	s_mov_b32 m0, s42
	s_nop 0
	buffer_load_dwordx4 v147, s[12:15], s58 offen lds
	s_add_i32 s29, s29, 2
	s_addk_i32 s56, 0x100
	s_addk_i32 s57, 0x100
	s_cmp_gt_u32 s29, 13
	s_waitcnt vmcnt(6)
	s_waitcnt lgkmcnt(0)
	s_cbranch_scc0 .LBB0_391
	s_setprio 1
	s_barrier
	v_mfma_f32_16x16x32_bf16 v[72:75], v[132:135], v[174:177], v[72:75]
	v_mfma_f32_16x16x32_bf16 v[60:63], v[140:143], v[174:177], v[60:63]
	v_mfma_f32_16x16x32_bf16 v[40:43], v[132:135], v[182:185], v[40:43]
	v_mfma_f32_16x16x32_bf16 v[32:35], v[140:143], v[182:185], v[32:35]
	v_mfma_f32_16x16x32_bf16 v[16:19], v[132:135], v[190:193], v[16:19]
	v_mfma_f32_16x16x32_bf16 v[12:15], v[140:143], v[190:193], v[12:15]
	v_mfma_f32_16x16x32_bf16 v[6:9], v[132:135], v[216:219], v[8:11]
	v_mfma_f32_16x16x32_bf16 v[2:5], v[140:143], v[216:219], v[2:5]
	v_mfma_f32_16x16x32_bf16 v[72:75], v[136:139], v[178:181], v[72:75]
	v_mfma_f32_16x16x32_bf16 v[60:63], v[154:157], v[178:181], v[60:63]
	v_mfma_f32_16x16x32_bf16 v[40:43], v[136:139], v[186:189], v[40:43]
	v_mfma_f32_16x16x32_bf16 v[32:35], v[154:157], v[186:189], v[32:35]
	v_mfma_f32_16x16x32_bf16 v[16:19], v[136:139], v[212:215], v[16:19]
	v_mfma_f32_16x16x32_bf16 v[12:15], v[154:157], v[212:215], v[12:15]
	v_mfma_f32_16x16x32_bf16 v[8:11], v[136:139], v[228:231], v[6:9]
	v_mfma_f32_16x16x32_bf16 v[4:7], v[154:157], v[228:231], v[2:5]
	v_mfma_f32_16x16x32_bf16 v[96:99], v[158:161], v[174:177], v[96:99]
	v_mfma_f32_16x16x32_bf16 v[104:107], v[166:169], v[174:177], v[104:107]
	v_mfma_f32_16x16x32_bf16 v[84:87], v[158:161], v[182:185], v[84:87]
	v_mfma_f32_16x16x32_bf16 v[76:79], v[166:169], v[182:185], v[76:79]
	v_mfma_f32_16x16x32_bf16 v[52:55], v[158:161], v[190:193], v[52:55]
	v_mfma_f32_16x16x32_bf16 v[44:47], v[166:169], v[190:193], v[44:47]
	v_mfma_f32_16x16x32_bf16 v[24:27], v[158:161], v[216:219], v[24:27]
	v_mfma_f32_16x16x32_bf16 v[20:23], v[166:169], v[216:219], v[20:23]
	v_mfma_f32_16x16x32_bf16 v[96:99], v[162:165], v[178:181], v[96:99]
	v_mfma_f32_16x16x32_bf16 v[104:107], v[170:173], v[178:181], v[104:107]
	v_mfma_f32_16x16x32_bf16 v[84:87], v[162:165], v[186:189], v[84:87]
	v_mfma_f32_16x16x32_bf16 v[76:79], v[170:173], v[186:189], v[76:79]
	v_mfma_f32_16x16x32_bf16 v[52:55], v[162:165], v[212:215], v[52:55]
	v_mfma_f32_16x16x32_bf16 v[44:47], v[170:173], v[212:215], v[44:47]
	v_mfma_f32_16x16x32_bf16 v[24:27], v[162:165], v[228:231], v[24:27]
	v_mfma_f32_16x16x32_bf16 v[20:23], v[170:173], v[228:231], v[20:23]
	s_barrier
	s_setprio 0
	s_mov_b32 m0, s41
	s_nop 0
	buffer_load_dwordx4 v144, s[16:19], s59 offen lds
	s_mov_b32 m0, s33
	s_nop 0
	buffer_load_dwordx4 v146, s[16:19], s59 offen lds
	v_readlane_b32 s8, v251, 45
	v_readlane_b32 s9, v251, 46
	s_and_b64 vcc, exec, s[8:9]
	s_cbranch_vccz .LBB0_394
	s_barrier

; template <class Epi, bool ALIGN_EPI, bool SP2, class Hook>
; __device__ __forceinline__ void gemm_phase(LAS unsigned char* lds, const Gemm g, const StaticOrder& S, const Epi& E, Acc& acc, const bool fresh, const Hook& H, const int wave_id) {
;     ...
; #pragma unroll
;             for (int a = 0; a < 2; ++a)
; #pragma unroll
;                 for (int b = 0; b < 2; ++b)
; #pragma unroll
;                     for (int m = 0; m < 4; ++m)
; #pragma unroll
;                         for (int n = 0; n < 2; ++n) acc[a][b][m][n] = (f32x4){0.f, 0.f, 0.f, 0.f};
.LBB0_902:
	v_mov_b32_e32 v178, 0
	s_add_i32 s55, s13, 0x20080
	s_add_i32 s56, s12, 0x100
	s_mov_b32 s57, -2
	v_mov_b32_e32 v179, v178
	v_mov_b32_e32 v180, v178
	v_mov_b32_e32 v181, v178
	v_mov_b32_e32 v170, v178
	v_mov_b32_e32 v171, v178
	v_mov_b32_e32 v172, v178
	v_mov_b32_e32 v173, v178
	v_mov_b32_e32 v150, v178
	v_mov_b32_e32 v151, v178
	v_mov_b32_e32 v152, v178
	v_mov_b32_e32 v153, v178
	v_mov_b32_e32 v146, v178
	v_mov_b32_e32 v147, v178
	v_mov_b32_e32 v148, v178
	v_mov_b32_e32 v149, v178
	v_mov_b32_e32 v126, v178
	v_mov_b32_e32 v127, v178
	v_mov_b32_e32 v128, v178
	v_mov_b32_e32 v129, v178
	v_mov_b32_e32 v122, v178
	v_mov_b32_e32 v123, v178
	v_mov_b32_e32 v124, v178
	v_mov_b32_e32 v125, v178
	v_mov_b32_e32 v102, v178
	v_mov_b32_e32 v103, v178
	v_mov_b32_e32 v104, v178
	v_mov_b32_e32 v105, v178
	v_mov_b32_e32 v98, v178
	v_mov_b32_e32 v99, v178
	v_mov_b32_e32 v100, v178
	v_mov_b32_e32 v101, v178
	v_mov_b32_e32 v162, v178
	v_mov_b32_e32 v163, v178
	v_mov_b32_e32 v164, v178
	v_mov_b32_e32 v165, v178
	v_mov_b32_e32 v158, v178
	v_mov_b32_e32 v159, v178
	v_mov_b32_e32 v160, v178
	v_mov_b32_e32 v161, v178
	v_mov_b32_e32 v138, v178
	v_mov_b32_e32 v139, v178
	v_mov_b32_e32 v140, v178
	v_mov_b32_e32 v141, v178
	v_mov_b32_e32 v134, v178
	v_mov_b32_e32 v135, v178
	v_mov_b32_e32 v136, v178
	v_mov_b32_e32 v137, v178
	v_mov_b32_e32 v114, v178
	v_mov_b32_e32 v115, v178
	v_mov_b32_e32 v116, v178
	v_mov_b32_e32 v117, v178
	v_mov_b32_e32 v110, v178
	v_mov_b32_e32 v111, v178
	v_mov_b32_e32 v112, v178
	v_mov_b32_e32 v113, v178
	v_mov_b32_e32 v90, v178
	v_mov_b32_e32 v91, v178
	v_mov_b32_e32 v92, v178
	v_mov_b32_e32 v93, v178
	v_mov_b32_e32 v86, v178
	v_mov_b32_e32 v87, v178
	v_mov_b32_e32 v88, v178
	v_mov_b32_e32 v89, v178
	v_mov_b32_e32 v78, v178
	v_mov_b32_e32 v79, v178
	v_mov_b32_e32 v80, v178
	v_mov_b32_e32 v81, v178
	v_mov_b32_e32 v74, v178
	v_mov_b32_e32 v75, v178
	v_mov_b32_e32 v76, v178
	v_mov_b32_e32 v77, v178
	v_mov_b32_e32 v54, v178
	v_mov_b32_e32 v55, v178
	v_mov_b32_e32 v56, v178
	v_mov_b32_e32 v57, v178
	v_mov_b32_e32 v50, v178
	v_mov_b32_e32 v51, v178
	v_mov_b32_e32 v52, v178
	v_mov_b32_e32 v53, v178
	v_mov_b32_e32 v30, v178
	v_mov_b32_e32 v31, v178
	v_mov_b32_e32 v32, v178
	v_mov_b32_e32 v33, v178
	v_mov_b32_e32 v26, v178
	v_mov_b32_e32 v27, v178
	v_mov_b32_e32 v28, v178
	v_mov_b32_e32 v29, v178
	v_mov_b32_e32 v14, v178
	v_mov_b32_e32 v15, v178
	v_mov_b32_e32 v16, v178
	v_mov_b32_e32 v17, v178
	v_mov_b32_e32 v10, v178
	v_mov_b32_e32 v11, v178
	v_mov_b32_e32 v12, v178
	v_mov_b32_e32 v13, v178
	v_mov_b32_e32 v66, v178
	v_mov_b32_e32 v67, v178
	v_mov_b32_e32 v68, v178
	v_mov_b32_e32 v69, v178
	v_mov_b32_e32 v62, v178
	v_mov_b32_e32 v63, v178
	v_mov_b32_e32 v64, v178
	v_mov_b32_e32 v65, v178
	v_mov_b32_e32 v42, v178
	v_mov_b32_e32 v43, v178
	v_mov_b32_e32 v44, v178
	v_mov_b32_e32 v45, v178
	v_mov_b32_e32 v38, v178
	v_mov_b32_e32 v39, v178
	v_mov_b32_e32 v40, v178
	v_mov_b32_e32 v41, v178
	v_mov_b32_e32 v22, v178
	v_mov_b32_e32 v23, v178
	v_mov_b32_e32 v24, v178
	v_mov_b32_e32 v25, v178
	v_mov_b32_e32 v18, v178
	v_mov_b32_e32 v19, v178
	v_mov_b32_e32 v20, v178
	v_mov_b32_e32 v21, v178
	v_mov_b32_e32 v6, v178
	v_mov_b32_e32 v7, v178
	v_mov_b32_e32 v8, v178
	v_mov_b32_e32 v9, v178
	v_mov_b32_e32 v2, v178
	v_mov_b32_e32 v3, v178
	v_mov_b32_e32 v4, v178
	v_mov_b32_e32 v5, v178
	s_branch .Lrot_in_4
.LBB0_903:
	s_setprio 1
	s_barrier
	v_mfma_f32_16x16x32_bf16 v[78:81], v[58:61], v[130:133], v[78:81]
	v_mfma_f32_16x16x32_bf16 v[74:77], v[66:69], v[130:133], v[74:77]
	v_mfma_f32_16x16x32_bf16 v[54:57], v[58:61], v[154:157], v[54:57]
	v_mfma_f32_16x16x32_bf16 v[50:53], v[66:69], v[154:157], v[50:53]
	v_mfma_f32_16x16x32_bf16 v[30:33], v[58:61], v[174:177], v[30:33]
	v_mfma_f32_16x16x32_bf16 v[26:29], v[66:69], v[174:177], v[26:29]
	v_mfma_f32_16x16x32_bf16 v[14:17], v[58:61], v[186:189], v[14:17]
	v_mfma_f32_16x16x32_bf16 v[10:13], v[66:69], v[186:189], v[10:13]
	v_mfma_f32_16x16x32_bf16 v[78:81], v[62:65], v[142:145], v[78:81]
	v_mfma_f32_16x16x32_bf16 v[74:77], v[70:73], v[142:145], v[74:77]
	v_mfma_f32_16x16x32_bf16 v[54:57], v[62:65], v[166:169], v[54:57]
	v_mfma_f32_16x16x32_bf16 v[50:53], v[70:73], v[166:169], v[50:53]
	v_mfma_f32_16x16x32_bf16 v[30:33], v[62:65], v[182:185], v[30:33]
	v_mfma_f32_16x16x32_bf16 v[26:29], v[70:73], v[182:185], v[26:29]
	v_mfma_f32_16x16x32_bf16 v[14:17], v[62:65], v[190:193], v[14:17]
	v_mfma_f32_16x16x32_bf16 v[10:13], v[70:73], v[190:193], v[10:13]
	v_mfma_f32_16x16x32_bf16 v[34:37], v[82:85], v[130:133], v[34:37]
	v_mfma_f32_16x16x32_bf16 v[66:69], v[94:97], v[142:145], v[34:37]
	v_mfma_f32_16x16x32_bf16 v[34:37], v[106:109], v[130:133], v[46:49]
	v_mfma_f32_16x16x32_bf16 v[62:65], v[118:121], v[142:145], v[34:37]
	v_mfma_f32_16x16x32_bf16 v[34:37], v[82:85], v[154:157], v[42:45]
	v_mfma_f32_16x16x32_bf16 v[42:45], v[94:97], v[166:169], v[34:37]
	v_mfma_f32_16x16x32_bf16 v[34:37], v[106:109], v[154:157], v[38:41]
	v_mfma_f32_16x16x32_bf16 v[22:25], v[82:85], v[174:177], v[22:25]
	v_mfma_f32_16x16x32_bf16 v[18:21], v[106:109], v[174:177], v[18:21]
	v_mfma_f32_16x16x32_bf16 v[6:9], v[82:85], v[186:189], v[6:9]
	v_mfma_f32_16x16x32_bf16 v[2:5], v[106:109], v[186:189], v[2:5]
	v_mfma_f32_16x16x32_bf16 v[38:41], v[118:121], v[166:169], v[34:37]
	v_mfma_f32_16x16x32_bf16 v[22:25], v[94:97], v[182:185], v[22:25]
	v_mfma_f32_16x16x32_bf16 v[18:21], v[118:121], v[182:185], v[18:21]
	v_mfma_f32_16x16x32_bf16 v[6:9], v[94:97], v[190:193], v[6:9]
	v_mfma_f32_16x16x32_bf16 v[2:5], v[118:121], v[190:193], v[2:5]
	s_barrier
	s_setprio 0
.Lrot_in_4:
	s_add_i32 s100, s55, 0xfffe0000
	v_add_u32_e32 v70, 0x10000, v216
	v_add_u32_e32 v118, 0x14000, v216
	ds_read_b128 v[34:37], v70
	ds_read_b128 v[46:49], v70 offset:1024
	ds_read_b128 v[58:61], v70 offset:2048
	ds_read_b128 v[70:73], v70 offset:3072
	ds_read_b128 v[82:85], v118
	ds_read_b128 v[94:97], v118 offset:1024
	ds_read_b128 v[106:109], v118 offset:2048
	ds_read_b128 v[118:121], v118 offset:3072
	s_mov_b32 m0, s41
	s_nop 0
	buffer_load_dwordx4 v0, s[8:11], s100 offen lds
	s_mov_b32 m0, s33
	s_nop 0
	buffer_load_dwordx4 v214, s[8:11], s100 offen lds
	s_mov_b32 m0, s45
	ds_read_b128 v[130:133], v217
	ds_read_b128 v[142:145], v217 offset:1024
	ds_read_b128 v[154:157], v217 offset:2048
	ds_read_b128 v[166:169], v217 offset:3072
	ds_read_b128 v[174:177], v217 offset:4096
	ds_read_b128 v[182:185], v217 offset:5120
	ds_read_b128 v[186:189], v217 offset:6144
	ds_read_b128 v[190:193], v217 offset:7168
	buffer_load_dwordx4 v0, s[8:11], s55 offen lds
	s_mov_b32 m0, s46
	s_nop 0
	buffer_load_dwordx4 v214, s[8:11], s55 offen lds
	s_waitcnt vmcnt(8)
	s_waitcnt lgkmcnt(0)
	s_setprio 1
	s_barrier
	v_mfma_f32_16x16x32_bf16 v[178:181], v[34:37], v[130:133], v[178:181]
	v_mfma_f32_16x16x32_bf16 v[170:173], v[58:61], v[130:133], v[170:173]
	v_mfma_f32_16x16x32_bf16 v[150:153], v[34:37], v[154:157], v[150:153]
	v_mfma_f32_16x16x32_bf16 v[146:149], v[58:61], v[154:157], v[146:149]
	v_mfma_f32_16x16x32_bf16 v[126:129], v[34:37], v[174:177], v[126:129]
	v_mfma_f32_16x16x32_bf16 v[122:125], v[58:61], v[174:177], v[122:125]
	v_mfma_f32_16x16x32_bf16 v[102:105], v[34:37], v[186:189], v[102:105]
	v_mfma_f32_16x16x32_bf16 v[98:101], v[58:61], v[186:189], v[98:101]
	v_mfma_f32_16x16x32_bf16 v[178:181], v[46:49], v[142:145], v[178:181]
	v_mfma_f32_16x16x32_bf16 v[170:173], v[70:73], v[142:145], v[170:173]
	v_mfma_f32_16x16x32_bf16 v[150:153], v[46:49], v[166:169], v[150:153]
	v_mfma_f32_16x16x32_bf16 v[146:149], v[70:73], v[166:169], v[146:149]
	v_mfma_f32_16x16x32_bf16 v[126:129], v[46:49], v[182:185], v[126:129]
	v_mfma_f32_16x16x32_bf16 v[122:125], v[70:73], v[182:185], v[122:125]
	v_mfma_f32_16x16x32_bf16 v[102:105], v[46:49], v[190:193], v[102:105]
	v_mfma_f32_16x16x32_bf16 v[98:101], v[70:73], v[190:193], v[98:101]
	v_mfma_f32_16x16x32_bf16 v[162:165], v[82:85], v[130:133], v[162:165]
	v_mfma_f32_16x16x32_bf16 v[138:141], v[82:85], v[154:157], v[138:141]
	v_mfma_f32_16x16x32_bf16 v[134:137], v[106:109], v[154:157], v[134:137]
	v_mfma_f32_16x16x32_bf16 v[114:117], v[82:85], v[174:177], v[114:117]
	v_mfma_f32_16x16x32_bf16 v[110:113], v[106:109], v[174:177], v[110:113]
	v_mfma_f32_16x16x32_bf16 v[90:93], v[82:85], v[186:189], v[90:93]
	v_mfma_f32_16x16x32_bf16 v[86:89], v[106:109], v[186:189], v[86:89]
	v_mfma_f32_16x16x32_bf16 v[162:165], v[94:97], v[142:145], v[162:165]
	v_mfma_f32_16x16x32_bf16 v[130:133], v[106:109], v[130:133], v[158:161]
	v_mfma_f32_16x16x32_bf16 v[138:141], v[94:97], v[166:169], v[138:141]
	v_mfma_f32_16x16x32_bf16 v[134:137], v[118:121], v[166:169], v[134:137]
	v_mfma_f32_16x16x32_bf16 v[114:117], v[94:97], v[182:185], v[114:117]
	v_mfma_f32_16x16x32_bf16 v[110:113], v[118:121], v[182:185], v[110:113]
	v_mfma_f32_16x16x32_bf16 v[90:93], v[94:97], v[190:193], v[90:93]
	v_mfma_f32_16x16x32_bf16 v[86:89], v[118:121], v[190:193], v[86:89]
	v_mfma_f32_16x16x32_bf16 v[130:133], v[118:121], v[142:145], v[130:133]
	s_barrier
	s_setprio 0
	s_add_i32 s12, s55, 0xfffe0080
	s_cmp_eq_u32 s57, 4
	s_cselect_b32 s60, s53, s12
	s_cselect_b32 s13, s29, s77
	s_cselect_b32 s12, s28, s76
	s_cselect_b32 s15, s31, s35
	s_cselect_b32 s14, s30, s34
	s_cselect_b32 s58, s54, s56
	s_cselect_b32 s16, s2, s8
	s_cselect_b32 s17, s3, s9
	s_cselect_b32 s18, s26, s10
	s_cselect_b32 s19, s27, s11
	s_or_b32 s59, s60, 0x80
	s_mov_b32 m0, s92
	ds_read_b128 v[142:145], v217 offset:16384
	ds_read_b128 v[154:157], v217 offset:17408
	ds_read_b128 v[158:161], v217 offset:18432
	ds_read_b128 v[166:169], v217 offset:19456
	ds_read_b128 v[174:177], v217 offset:20480
	ds_read_b128 v[182:185], v217 offset:21504
	ds_read_b128 v[186:189], v217 offset:22528
	ds_read_b128 v[190:193], v217 offset:23552
	buffer_load_dwordx4 v199, s[12:15], s58 offen lds
	s_mov_b32 m0, s93
	s_add_i32 s61, s58, 0x20000
	buffer_load_dwordx4 v215, s[12:15], s58 offen lds
	s_mov_b32 m0, s94
	s_nop 0
	buffer_load_dwordx4 v199, s[12:15], s61 offen lds
	s_mov_b32 m0, s95
	s_nop 0
	buffer_load_dwordx4 v215, s[12:15], s61 offen lds
	s_waitcnt vmcnt(6)
	s_waitcnt lgkmcnt(0)
	s_setprio 1
	s_barrier
	v_mfma_f32_16x16x32_bf16 v[78:81], v[34:37], v[142:145], v[78:81]
	v_mfma_f32_16x16x32_bf16 v[74:77], v[58:61], v[142:145], v[74:77]
	v_mfma_f32_16x16x32_bf16 v[54:57], v[34:37], v[158:161], v[54:57]
	v_mfma_f32_16x16x32_bf16 v[50:53], v[58:61], v[158:161], v[50:53]
	v_mfma_f32_16x16x32_bf16 v[30:33], v[34:37], v[174:177], v[30:33]
	v_mfma_f32_16x16x32_bf16 v[26:29], v[58:61], v[174:177], v[26:29]
	v_mfma_f32_16x16x32_bf16 v[14:17], v[34:37], v[186:189], v[14:17]
	v_mfma_f32_16x16x32_bf16 v[10:13], v[58:61], v[186:189], v[10:13]
	v_mfma_f32_16x16x32_bf16 v[78:81], v[46:49], v[154:157], v[78:81]
	v_mfma_f32_16x16x32_bf16 v[74:77], v[70:73], v[154:157], v[74:77]
	v_mfma_f32_16x16x32_bf16 v[54:57], v[46:49], v[166:169], v[54:57]
	v_mfma_f32_16x16x32_bf16 v[50:53], v[70:73], v[166:169], v[50:53]
	v_mfma_f32_16x16x32_bf16 v[30:33], v[46:49], v[182:185], v[30:33]
	v_mfma_f32_16x16x32_bf16 v[26:29], v[70:73], v[182:185], v[26:29]
	v_mfma_f32_16x16x32_bf16 v[14:17], v[46:49], v[190:193], v[14:17]
	v_mfma_f32_16x16x32_bf16 v[10:13], v[70:73], v[190:193], v[10:13]
	v_mfma_f32_16x16x32_bf16 v[42:45], v[82:85], v[158:161], v[42:45]
	v_mfma_f32_16x16x32_bf16 v[38:41], v[106:109], v[158:161], v[38:41]
	v_mfma_f32_16x16x32_bf16 v[22:25], v[82:85], v[174:177], v[22:25]
	v_mfma_f32_16x16x32_bf16 v[18:21], v[106:109], v[174:177], v[18:21]
	v_mfma_f32_16x16x32_bf16 v[6:9], v[82:85], v[186:189], v[6:9]
	v_mfma_f32_16x16x32_bf16 v[2:5], v[106:109], v[186:189], v[2:5]
	v_mfma_f32_16x16x32_bf16 v[34:37], v[82:85], v[142:145], v[66:69]
	v_mfma_f32_16x16x32_bf16 v[46:49], v[106:109], v[142:145], v[62:65]
	v_mfma_f32_16x16x32_bf16 v[42:45], v[94:97], v[166:169], v[42:45]
	v_mfma_f32_16x16x32_bf16 v[38:41], v[118:121], v[166:169], v[38:41]
	v_mfma_f32_16x16x32_bf16 v[22:25], v[94:97], v[182:185], v[22:25]
	v_mfma_f32_16x16x32_bf16 v[18:21], v[118:121], v[182:185], v[18:21]
	v_mfma_f32_16x16x32_bf16 v[6:9], v[94:97], v[190:193], v[6:9]
	v_mfma_f32_16x16x32_bf16 v[2:5], v[118:121], v[190:193], v[2:5]
	v_mfma_f32_16x16x32_bf16 v[34:37], v[94:97], v[154:157], v[34:37]
	v_mfma_f32_16x16x32_bf16 v[46:49], v[118:121], v[154:157], v[46:49]
	s_barrier
	s_setprio 0
	s_mov_b32 m0, s44
	s_nop 0
	buffer_load_dwordx4 v0, s[16:19], s60 offen lds
	s_mov_b32 m0, s36
	s_nop 0
	buffer_load_dwordx4 v214, s[16:19], s60 offen lds
	v_add_u32_e32 v70, 0x18000, v216
	v_add_u32_e32 v118, 0x1c000, v216
	ds_read_b128 v[58:61], v70
	ds_read_b128 v[62:65], v70 offset:1024
	ds_read_b128 v[66:69], v70 offset:2048
	ds_read_b128 v[70:73], v70 offset:3072
	ds_read_b128 v[82:85], v118
	ds_read_b128 v[94:97], v118 offset:1024
	ds_read_b128 v[106:109], v118 offset:2048
	ds_read_b128 v[118:121], v118 offset:3072
	s_add_i32 s60, s60, 0x20000
	s_mov_b32 m0, s37
	ds_read_b128 v[142:145], v217 offset:32768
	ds_read_b128 v[154:157], v217 offset:33792
	ds_read_b128 v[166:169], v217 offset:34816
	ds_read_b128 v[174:177], v217 offset:35840
	ds_read_b128 v[182:185], v217 offset:36864
	ds_read_b128 v[186:189], v217 offset:37888
	ds_read_b128 v[190:193], v217 offset:38912
	ds_read_b128 v[194:197], v217 offset:39936
	buffer_load_dwordx4 v0, s[16:19], s60 offen lds
	s_mov_b32 m0, s38
	s_nop 0
	buffer_load_dwordx4 v214, s[16:19], s60 offen lds
	s_waitcnt vmcnt(8)
	s_waitcnt lgkmcnt(0)
	s_setprio 1
	s_barrier
	v_mfma_f32_16x16x32_bf16 v[158:161], v[58:61], v[142:145], v[178:181]
	v_mfma_f32_16x16x32_bf16 v[178:181], v[62:65], v[154:157], v[158:161]
	v_mfma_f32_16x16x32_bf16 v[158:161], v[66:69], v[142:145], v[170:173]
	v_mfma_f32_16x16x32_bf16 v[150:153], v[58:61], v[166:169], v[150:153]
	v_mfma_f32_16x16x32_bf16 v[146:149], v[66:69], v[166:169], v[146:149]
	v_mfma_f32_16x16x32_bf16 v[126:129], v[58:61], v[182:185], v[126:129]
	v_mfma_f32_16x16x32_bf16 v[122:125], v[66:69], v[182:185], v[122:125]
	v_mfma_f32_16x16x32_bf16 v[102:105], v[58:61], v[190:193], v[102:105]
	v_mfma_f32_16x16x32_bf16 v[98:101], v[66:69], v[190:193], v[98:101]
	v_mfma_f32_16x16x32_bf16 v[170:173], v[70:73], v[154:157], v[158:161]
	v_mfma_f32_16x16x32_bf16 v[150:153], v[62:65], v[174:177], v[150:153]
	v_mfma_f32_16x16x32_bf16 v[146:149], v[70:73], v[174:177], v[146:149]
	v_mfma_f32_16x16x32_bf16 v[126:129], v[62:65], v[186:189], v[126:129]
	v_mfma_f32_16x16x32_bf16 v[122:125], v[70:73], v[186:189], v[122:125]
	v_mfma_f32_16x16x32_bf16 v[102:105], v[62:65], v[194:197], v[102:105]
	v_mfma_f32_16x16x32_bf16 v[98:101], v[70:73], v[194:197], v[98:101]
	v_mfma_f32_16x16x32_bf16 v[158:161], v[82:85], v[142:145], v[162:165]
	v_mfma_f32_16x16x32_bf16 v[130:133], v[106:109], v[142:145], v[130:133]
	v_mfma_f32_16x16x32_bf16 v[162:165], v[94:97], v[154:157], v[158:161]
	v_mfma_f32_16x16x32_bf16 v[158:161], v[118:121], v[154:157], v[130:133]
	v_mfma_f32_16x16x32_bf16 v[130:133], v[82:85], v[166:169], v[138:141]
	v_mfma_f32_16x16x32_bf16 v[138:141], v[94:97], v[174:177], v[130:133]
	v_mfma_f32_16x16x32_bf16 v[130:133], v[106:109], v[166:169], v[134:137]
	v_mfma_f32_16x16x32_bf16 v[114:117], v[82:85], v[182:185], v[114:117]
	v_mfma_f32_16x16x32_bf16 v[110:113], v[106:109], v[182:185], v[110:113]
	v_mfma_f32_16x16x32_bf16 v[90:93], v[82:85], v[190:193], v[90:93]
	v_mfma_f32_16x16x32_bf16 v[86:89], v[106:109], v[190:193], v[86:89]
	v_mfma_f32_16x16x32_bf16 v[134:137], v[118:121], v[174:177], v[130:133]
	v_mfma_f32_16x16x32_bf16 v[114:117], v[94:97], v[186:189], v[114:117]
	v_mfma_f32_16x16x32_bf16 v[110:113], v[118:121], v[186:189], v[110:113]
	v_mfma_f32_16x16x32_bf16 v[90:93], v[94:97], v[194:197], v[90:93]
	v_mfma_f32_16x16x32_bf16 v[86:89], v[118:121], v[194:197], v[86:89]
	s_barrier
	s_setprio 0
	s_mov_b32 m0, s39
	s_or_b32 s60, s58, 0x80
	ds_read_b128 v[130:133], v217 offset:49152
	ds_read_b128 v[142:145], v217 offset:50176
	ds_read_b128 v[154:157], v217 offset:51200
	ds_read_b128 v[166:169], v217 offset:52224
	ds_read_b128 v[174:177], v217 offset:53248
	ds_read_b128 v[182:185], v217 offset:54272
	ds_read_b128 v[186:189], v217 offset:55296
	ds_read_b128 v[190:193], v217 offset:56320
	buffer_load_dwordx4 v199, s[12:15], s60 offen lds
	s_mov_b32 m0, s40
	s_add_i32 s58, s58, 0x20080
	buffer_load_dwordx4 v215, s[12:15], s60 offen lds
	s_mov_b32 m0, s43
	s_nop 0
	buffer_load_dwordx4 v199, s[12:15], s58 offen lds
	s_mov_b32 m0, s42
	s_nop 0
	buffer_load_dwordx4 v215, s[12:15], s58 offen lds
	s_add_i32 s57, s57, 2
	s_addk_i32 s55, 0x100
	s_addk_i32 s56, 0x100
	s_cmp_gt_u32 s57, 5
	s_waitcnt vmcnt(6)
	s_waitcnt lgkmcnt(0)
	s_cbranch_scc0 .LBB0_903
	s_setprio 1
	s_barrier
	v_mfma_f32_16x16x32_bf16 v[78:81], v[58:61], v[130:133], v[78:81]
	v_mfma_f32_16x16x32_bf16 v[74:77], v[66:69], v[130:133], v[74:77]
	v_mfma_f32_16x16x32_bf16 v[54:57], v[58:61], v[154:157], v[54:57]
	v_mfma_f32_16x16x32_bf16 v[50:53], v[66:69], v[154:157], v[50:53]
	v_mfma_f32_16x16x32_bf16 v[30:33], v[58:61], v[174:177], v[30:33]
	v_mfma_f32_16x16x32_bf16 v[26:29], v[66:69], v[174:177], v[26:29]
	v_mfma_f32_16x16x32_bf16 v[14:17], v[58:61], v[186:189], v[14:17]
	v_mfma_f32_16x16x32_bf16 v[10:13], v[66:69], v[186:189], v[10:13]
	v_mfma_f32_16x16x32_bf16 v[78:81], v[62:65], v[142:145], v[78:81]
	v_mfma_f32_16x16x32_bf16 v[74:77], v[70:73], v[142:145], v[74:77]
	v_mfma_f32_16x16x32_bf16 v[54:57], v[62:65], v[166:169], v[54:57]
	v_mfma_f32_16x16x32_bf16 v[50:53], v[70:73], v[166:169], v[50:53]
	v_mfma_f32_16x16x32_bf16 v[30:33], v[62:65], v[182:185], v[30:33]
	v_mfma_f32_16x16x32_bf16 v[26:29], v[70:73], v[182:185], v[26:29]
	v_mfma_f32_16x16x32_bf16 v[14:17], v[62:65], v[190:193], v[14:17]
	v_mfma_f32_16x16x32_bf16 v[10:13], v[70:73], v[190:193], v[10:13]
	v_mfma_f32_16x16x32_bf16 v[34:37], v[82:85], v[130:133], v[34:37]
	v_mfma_f32_16x16x32_bf16 v[66:69], v[94:97], v[142:145], v[34:37]
	v_mfma_f32_16x16x32_bf16 v[34:37], v[106:109], v[130:133], v[46:49]
	v_mfma_f32_16x16x32_bf16 v[62:65], v[118:121], v[142:145], v[34:37]
	v_mfma_f32_16x16x32_bf16 v[34:37], v[82:85], v[154:157], v[42:45]
	v_mfma_f32_16x16x32_bf16 v[42:45], v[94:97], v[166:169], v[34:37]
	v_mfma_f32_16x16x32_bf16 v[34:37], v[106:109], v[154:157], v[38:41]
	v_mfma_f32_16x16x32_bf16 v[22:25], v[82:85], v[174:177], v[22:25]
	v_mfma_f32_16x16x32_bf16 v[18:21], v[106:109], v[174:177], v[18:21]
	v_mfma_f32_16x16x32_bf16 v[6:9], v[82:85], v[186:189], v[6:9]
	v_mfma_f32_16x16x32_bf16 v[2:5], v[106:109], v[186:189], v[2:5]
	v_mfma_f32_16x16x32_bf16 v[38:41], v[118:121], v[166:169], v[34:37]
	v_mfma_f32_16x16x32_bf16 v[22:25], v[94:97], v[182:185], v[22:25]
	v_mfma_f32_16x16x32_bf16 v[18:21], v[118:121], v[182:185], v[18:21]
	v_mfma_f32_16x16x32_bf16 v[6:9], v[94:97], v[190:193], v[6:9]
	v_mfma_f32_16x16x32_bf16 v[2:5], v[118:121], v[190:193], v[2:5]
	s_barrier
	s_setprio 0
	s_mov_b32 m0, s41
	s_nop 0
	buffer_load_dwordx4 v0, s[16:19], s59 offen lds
	s_mov_b32 m0, s33
	s_nop 0
	buffer_load_dwordx4 v214, s[16:19], s59 offen lds
	v_readlane_b32 s8, v251, 45
	v_readlane_b32 s9, v251, 46
	s_and_b64 vcc, exec, s[8:9]
	s_cbranch_vccz .LBB0_906
	s_barrier

; template <class Epi, bool ALIGN_EPI, bool SP2, class Hook>
; __device__ __forceinline__ void gemm_phase(LAS unsigned char* lds, const Gemm g, const StaticOrder& S, const Epi& E, Acc& acc, const bool fresh, const Hook& H, const int wave_id) {
;     ...
; #pragma unroll
;             for (int a = 0; a < 2; ++a)
; #pragma unroll
;                 for (int b = 0; b < 2; ++b)
; #pragma unroll
;                     for (int m = 0; m < 4; ++m)
; #pragma unroll
;                         for (int n = 0; n < 2; ++n) acc[a][b][m][n] = (f32x4){0.f, 0.f, 0.f, 0.f};
.LBB0_1234:
	v_mov_b32_e32 v2, 0
	s_add_i32 s2, s17, 0x40080
	s_add_i32 s3, s16, 0x100
	s_mov_b32 s59, -2
	v_mov_b32_e32 v3, v2
	v_mov_b32_e32 v4, v2
	v_mov_b32_e32 v5, v2
	v_mov_b32_e32 v6, v2
	v_mov_b32_e32 v7, v2
	v_mov_b32_e32 v8, v2
	v_mov_b32_e32 v9, v2
	v_mov_b32_e32 v18, v2
	v_mov_b32_e32 v19, v2
	v_mov_b32_e32 v20, v2
	v_mov_b32_e32 v21, v2
	v_mov_b32_e32 v22, v2
	v_mov_b32_e32 v23, v2
	v_mov_b32_e32 v24, v2
	v_mov_b32_e32 v25, v2
	v_mov_b32_e32 v34, v2
	v_mov_b32_e32 v35, v2
	v_mov_b32_e32 v36, v2
	v_mov_b32_e32 v37, v2
	v_mov_b32_e32 v38, v2
	v_mov_b32_e32 v39, v2
	v_mov_b32_e32 v40, v2
	v_mov_b32_e32 v41, v2
	v_mov_b32_e32 v50, v2
	v_mov_b32_e32 v51, v2
	v_mov_b32_e32 v52, v2
	v_mov_b32_e32 v53, v2
	v_mov_b32_e32 v54, v2
	v_mov_b32_e32 v55, v2
	v_mov_b32_e32 v56, v2
	v_mov_b32_e32 v57, v2
	v_mov_b32_e32 v10, v2
	v_mov_b32_e32 v11, v2
	v_mov_b32_e32 v12, v2
	v_mov_b32_e32 v13, v2
	v_mov_b32_e32 v14, v2
	v_mov_b32_e32 v15, v2
	v_mov_b32_e32 v16, v2
	v_mov_b32_e32 v17, v2
	v_mov_b32_e32 v26, v2
	v_mov_b32_e32 v27, v2
	v_mov_b32_e32 v28, v2
	v_mov_b32_e32 v29, v2
	v_mov_b32_e32 v30, v2
	v_mov_b32_e32 v31, v2
	v_mov_b32_e32 v32, v2
	v_mov_b32_e32 v33, v2
	v_mov_b32_e32 v42, v2
	v_mov_b32_e32 v43, v2
	v_mov_b32_e32 v44, v2
	v_mov_b32_e32 v45, v2
	v_mov_b32_e32 v46, v2
	v_mov_b32_e32 v47, v2
	v_mov_b32_e32 v48, v2
	v_mov_b32_e32 v49, v2
	v_mov_b32_e32 v58, v2
	v_mov_b32_e32 v59, v2
	v_mov_b32_e32 v60, v2
	v_mov_b32_e32 v61, v2
	v_mov_b32_e32 v62, v2
	v_mov_b32_e32 v63, v2
	v_mov_b32_e32 v64, v2
	v_mov_b32_e32 v65, v2
	v_mov_b32_e32 v66, v2
	v_mov_b32_e32 v67, v2
	v_mov_b32_e32 v68, v2
	v_mov_b32_e32 v69, v2
	v_mov_b32_e32 v70, v2
	v_mov_b32_e32 v71, v2
	v_mov_b32_e32 v72, v2
	v_mov_b32_e32 v73, v2
	v_mov_b32_e32 v82, v2
	v_mov_b32_e32 v83, v2
	v_mov_b32_e32 v84, v2
	v_mov_b32_e32 v85, v2
	v_mov_b32_e32 v86, v2
	v_mov_b32_e32 v87, v2
	v_mov_b32_e32 v88, v2
	v_mov_b32_e32 v89, v2
	v_mov_b32_e32 v98, v2
	v_mov_b32_e32 v99, v2
	v_mov_b32_e32 v100, v2
	v_mov_b32_e32 v101, v2
	v_mov_b32_e32 v102, v2
	v_mov_b32_e32 v103, v2
	v_mov_b32_e32 v104, v2
	v_mov_b32_e32 v105, v2
	v_mov_b32_e32 v114, v2
	v_mov_b32_e32 v115, v2
	v_mov_b32_e32 v116, v2
	v_mov_b32_e32 v117, v2
	v_mov_b32_e32 v118, v2
	v_mov_b32_e32 v119, v2
	v_mov_b32_e32 v120, v2
	v_mov_b32_e32 v121, v2
	v_mov_b32_e32 v74, v2
	v_mov_b32_e32 v75, v2
	v_mov_b32_e32 v76, v2
	v_mov_b32_e32 v77, v2
	v_mov_b32_e32 v78, v2
	v_mov_b32_e32 v79, v2
	v_mov_b32_e32 v80, v2
	v_mov_b32_e32 v81, v2
	v_mov_b32_e32 v90, v2
	v_mov_b32_e32 v91, v2
	v_mov_b32_e32 v92, v2
	v_mov_b32_e32 v93, v2
	v_mov_b32_e32 v94, v2
	v_mov_b32_e32 v95, v2
	v_mov_b32_e32 v96, v2
	v_mov_b32_e32 v97, v2
	v_mov_b32_e32 v106, v2
	v_mov_b32_e32 v107, v2
	v_mov_b32_e32 v108, v2
	v_mov_b32_e32 v109, v2
	v_mov_b32_e32 v110, v2
	v_mov_b32_e32 v111, v2
	v_mov_b32_e32 v112, v2
	v_mov_b32_e32 v113, v2
	v_mov_b32_e32 v122, v2
	v_mov_b32_e32 v123, v2
	v_mov_b32_e32 v124, v2
	v_mov_b32_e32 v125, v2
	v_mov_b32_e32 v126, v2
	v_mov_b32_e32 v127, v2
	v_mov_b32_e32 v128, v2
	v_mov_b32_e32 v129, v2
	s_branch .Lrot_in_6
.LBB0_1235:
	s_setprio 1
	s_barrier
	v_mfma_f32_16x16x32_bf16 v[62:65], v[130:133], v[168:171], v[62:65]
	v_mfma_f32_16x16x32_bf16 v[58:61], v[138:141], v[168:171], v[58:61]
	v_mfma_f32_16x16x32_bf16 v[46:49], v[130:133], v[176:179], v[46:49]
	v_mfma_f32_16x16x32_bf16 v[42:45], v[138:141], v[176:179], v[42:45]
	v_mfma_f32_16x16x32_bf16 v[30:33], v[130:133], v[184:187], v[30:33]
	v_mfma_f32_16x16x32_bf16 v[26:29], v[138:141], v[184:187], v[26:29]
	v_mfma_f32_16x16x32_bf16 v[14:17], v[130:133], v[192:195], v[14:17]
	v_mfma_f32_16x16x32_bf16 v[10:13], v[138:141], v[192:195], v[10:13]
	v_mfma_f32_16x16x32_bf16 v[62:65], v[134:137], v[172:175], v[62:65]
	v_mfma_f32_16x16x32_bf16 v[58:61], v[142:145], v[172:175], v[58:61]
	v_mfma_f32_16x16x32_bf16 v[46:49], v[134:137], v[180:183], v[46:49]
	v_mfma_f32_16x16x32_bf16 v[42:45], v[142:145], v[180:183], v[42:45]
	v_mfma_f32_16x16x32_bf16 v[30:33], v[134:137], v[188:191], v[30:33]
	v_mfma_f32_16x16x32_bf16 v[26:29], v[142:145], v[188:191], v[26:29]
	v_mfma_f32_16x16x32_bf16 v[14:17], v[134:137], v[200:203], v[14:17]
	v_mfma_f32_16x16x32_bf16 v[10:13], v[142:145], v[200:203], v[10:13]
	v_mfma_f32_16x16x32_bf16 v[54:57], v[146:149], v[168:171], v[54:57]
	v_mfma_f32_16x16x32_bf16 v[50:53], v[154:157], v[168:171], v[50:53]
	v_mfma_f32_16x16x32_bf16 v[38:41], v[146:149], v[176:179], v[38:41]
	v_mfma_f32_16x16x32_bf16 v[34:37], v[154:157], v[176:179], v[34:37]
	v_mfma_f32_16x16x32_bf16 v[22:25], v[146:149], v[184:187], v[22:25]
	v_mfma_f32_16x16x32_bf16 v[18:21], v[154:157], v[184:187], v[18:21]
	v_mfma_f32_16x16x32_bf16 v[6:9], v[146:149], v[192:195], v[6:9]
	v_mfma_f32_16x16x32_bf16 v[2:5], v[154:157], v[192:195], v[2:5]
	v_mfma_f32_16x16x32_bf16 v[54:57], v[150:153], v[172:175], v[54:57]
	v_mfma_f32_16x16x32_bf16 v[50:53], v[164:167], v[172:175], v[50:53]
	v_mfma_f32_16x16x32_bf16 v[38:41], v[150:153], v[180:183], v[38:41]
	v_mfma_f32_16x16x32_bf16 v[34:37], v[164:167], v[180:183], v[34:37]
	v_mfma_f32_16x16x32_bf16 v[22:25], v[150:153], v[188:191], v[22:25]
	v_mfma_f32_16x16x32_bf16 v[18:21], v[164:167], v[188:191], v[18:21]
	v_mfma_f32_16x16x32_bf16 v[6:9], v[150:153], v[200:203], v[6:9]
	v_mfma_f32_16x16x32_bf16 v[2:5], v[164:167], v[200:203], v[2:5]
	s_barrier
	s_setprio 0
; template <class Epi, bool ALIGN_EPI, bool SP2, class Hook>
; __device__ __forceinline__ void gemm_phase(LAS unsigned char* lds, const Gemm g, const StaticOrder& S, const Epi& E, Acc& acc, const bool fresh, const Hook& H, const int wave_id) {
;     ...
;         for (int t = t0; t < nt; t += 2) {
;             const bool last = (t == nt - 2);
;             const Src a1 = cA + (size_t)(t + 1) * kstep;
;             const Src a2 = last ? nA : cA + (size_t)(t + 2) * kstep, b2 = last ? nB : cB + (size_t)(t + 2) * kstep;
;             const Src a3 = a2 + kstep, b3 = b2 + kstep;
.Lrot_in_6:
	s_add_i32 s100, s2, 0xfffc0000
	v_add_u32_e32 v142, 0x10000, v161
	v_add_u32_e32 v163, 0x14000, v161
	ds_read_b128 v[130:133], v142
	ds_read_b128 v[134:137], v142 offset:1024
	ds_read_b128 v[138:141], v142 offset:2048
	ds_read_b128 v[142:145], v142 offset:3072
	ds_read_b128 v[146:149], v163
	ds_read_b128 v[150:153], v163 offset:1024
	ds_read_b128 v[154:157], v163 offset:2048
	ds_read_b128 v[164:167], v163 offset:3072
	s_mov_b32 m0, s41
	s_nop 0
	buffer_load_dwordx4 v0, s[12:15], s100 offen lds
	s_mov_b32 m0, s33
	s_nop 0
	buffer_load_dwordx4 v159, s[12:15], s100 offen lds
	s_mov_b32 m0, s45
	ds_read_b128 v[168:171], v162
	ds_read_b128 v[172:175], v162 offset:1024
	ds_read_b128 v[176:179], v162 offset:2048
	ds_read_b128 v[180:183], v162 offset:3072
	ds_read_b128 v[184:187], v162 offset:4096
	ds_read_b128 v[188:191], v162 offset:5120
	ds_read_b128 v[192:195], v162 offset:6144
	ds_read_b128 v[200:203], v162 offset:7168
	buffer_load_dwordx4 v0, s[12:15], s2 offen lds
	s_mov_b32 m0, s46
	s_nop 0
	buffer_load_dwordx4 v159, s[12:15], s2 offen lds
	s_waitcnt vmcnt(8)
	s_waitcnt lgkmcnt(0)
	s_setprio 1
	s_barrier
	v_mfma_f32_16x16x32_bf16 v[126:129], v[130:133], v[168:171], v[126:129]
	v_mfma_f32_16x16x32_bf16 v[122:125], v[138:141], v[168:171], v[122:125]
	v_mfma_f32_16x16x32_bf16 v[110:113], v[130:133], v[176:179], v[110:113]
	v_mfma_f32_16x16x32_bf16 v[106:109], v[138:141], v[176:179], v[106:109]
	v_mfma_f32_16x16x32_bf16 v[94:97], v[130:133], v[184:187], v[94:97]
	v_mfma_f32_16x16x32_bf16 v[90:93], v[138:141], v[184:187], v[90:93]
	v_mfma_f32_16x16x32_bf16 v[78:81], v[130:133], v[192:195], v[78:81]
	v_mfma_f32_16x16x32_bf16 v[74:77], v[138:141], v[192:195], v[74:77]
	v_mfma_f32_16x16x32_bf16 v[126:129], v[134:137], v[172:175], v[126:129]
	v_mfma_f32_16x16x32_bf16 v[122:125], v[142:145], v[172:175], v[122:125]
	v_mfma_f32_16x16x32_bf16 v[110:113], v[134:137], v[180:183], v[110:113]
	v_mfma_f32_16x16x32_bf16 v[106:109], v[142:145], v[180:183], v[106:109]
	v_mfma_f32_16x16x32_bf16 v[94:97], v[134:137], v[188:191], v[94:97]
	v_mfma_f32_16x16x32_bf16 v[90:93], v[142:145], v[188:191], v[90:93]
	v_mfma_f32_16x16x32_bf16 v[78:81], v[134:137], v[200:203], v[78:81]
	v_mfma_f32_16x16x32_bf16 v[74:77], v[142:145], v[200:203], v[74:77]
	v_mfma_f32_16x16x32_bf16 v[118:121], v[146:149], v[168:171], v[118:121]
	v_mfma_f32_16x16x32_bf16 v[114:117], v[154:157], v[168:171], v[114:117]
	v_mfma_f32_16x16x32_bf16 v[102:105], v[146:149], v[176:179], v[102:105]
	v_mfma_f32_16x16x32_bf16 v[98:101], v[154:157], v[176:179], v[98:101]
	v_mfma_f32_16x16x32_bf16 v[86:89], v[146:149], v[184:187], v[86:89]
	v_mfma_f32_16x16x32_bf16 v[82:85], v[154:157], v[184:187], v[82:85]
	v_mfma_f32_16x16x32_bf16 v[70:73], v[146:149], v[192:195], v[70:73]
	v_mfma_f32_16x16x32_bf16 v[66:69], v[154:157], v[192:195], v[66:69]
	v_mfma_f32_16x16x32_bf16 v[118:121], v[150:153], v[172:175], v[118:121]
	v_mfma_f32_16x16x32_bf16 v[114:117], v[164:167], v[172:175], v[114:117]
	v_mfma_f32_16x16x32_bf16 v[102:105], v[150:153], v[180:183], v[102:105]
	v_mfma_f32_16x16x32_bf16 v[98:101], v[164:167], v[180:183], v[98:101]
	v_mfma_f32_16x16x32_bf16 v[86:89], v[150:153], v[188:191], v[86:89]
	v_mfma_f32_16x16x32_bf16 v[82:85], v[164:167], v[188:191], v[82:85]
	v_mfma_f32_16x16x32_bf16 v[70:73], v[150:153], v[200:203], v[70:73]
	v_mfma_f32_16x16x32_bf16 v[66:69], v[164:167], v[200:203], v[66:69]
	s_barrier
	s_setprio 0
	s_add_i32 s16, s2, 0xfffc0080
	s_cmp_eq_u32 s59, 12
	s_cselect_b32 s62, s55, s16
	s_cselect_b32 s17, s31, s9
	s_cselect_b32 s16, s30, s8
	s_cselect_b32 s19, s35, s51
	s_cselect_b32 s18, s34, s50
	s_cselect_b32 s60, s56, s3
	s_cselect_b32 s20, s26, s12
	s_cselect_b32 s21, s27, s13
	s_cselect_b32 s22, s28, s14
	s_cselect_b32 s23, s29, s15
	s_or_b32 s61, s62, 0x80
	s_mov_b32 m0, s92
	ds_read_b128 v[168:171], v162 offset:16384
	ds_read_b128 v[172:175], v162 offset:17408
	ds_read_b128 v[176:179], v162 offset:18432
	ds_read_b128 v[180:183], v162 offset:19456
	ds_read_b128 v[184:187], v162 offset:20480
	ds_read_b128 v[188:191], v162 offset:21504
	ds_read_b128 v[192:195], v162 offset:22528
	ds_read_b128 v[200:203], v162 offset:23552
	buffer_load_dwordx4 v158, s[16:19], s60 offen lds
	s_mov_b32 m0, s93
	s_add_i32 s63, s60, 0x40000
	buffer_load_dwordx4 v160, s[16:19], s60 offen lds
	s_mov_b32 m0, s94
	s_nop 0
	buffer_load_dwordx4 v158, s[16:19], s63 offen lds
	s_mov_b32 m0, s95
	s_nop 0
	buffer_load_dwordx4 v160, s[16:19], s63 offen lds
	s_waitcnt vmcnt(6)
	s_waitcnt lgkmcnt(0)
	s_setprio 1
	s_barrier
	v_mfma_f32_16x16x32_bf16 v[62:65], v[130:133], v[168:171], v[62:65]
	v_mfma_f32_16x16x32_bf16 v[58:61], v[138:141], v[168:171], v[58:61]
	v_mfma_f32_16x16x32_bf16 v[46:49], v[130:133], v[176:179], v[46:49]
	v_mfma_f32_16x16x32_bf16 v[42:45], v[138:141], v[176:179], v[42:45]
	v_mfma_f32_16x16x32_bf16 v[30:33], v[130:133], v[184:187], v[30:33]
	v_mfma_f32_16x16x32_bf16 v[26:29], v[138:141], v[184:187], v[26:29]
	v_mfma_f32_16x16x32_bf16 v[14:17], v[130:133], v[192:195], v[14:17]
	v_mfma_f32_16x16x32_bf16 v[10:13], v[138:141], v[192:195], v[10:13]
	v_mfma_f32_16x16x32_bf16 v[62:65], v[134:137], v[172:175], v[62:65]
	v_mfma_f32_16x16x32_bf16 v[58:61], v[142:145], v[172:175], v[58:61]
	v_mfma_f32_16x16x32_bf16 v[46:49], v[134:137], v[180:183], v[46:49]
	v_mfma_f32_16x16x32_bf16 v[42:45], v[142:145], v[180:183], v[42:45]
	v_mfma_f32_16x16x32_bf16 v[30:33], v[134:137], v[188:191], v[30:33]
	v_mfma_f32_16x16x32_bf16 v[26:29], v[142:145], v[188:191], v[26:29]
	v_mfma_f32_16x16x32_bf16 v[14:17], v[134:137], v[200:203], v[14:17]
	v_mfma_f32_16x16x32_bf16 v[10:13], v[142:145], v[200:203], v[10:13]
	v_mfma_f32_16x16x32_bf16 v[54:57], v[146:149], v[168:171], v[54:57]
	v_mfma_f32_16x16x32_bf16 v[50:53], v[154:157], v[168:171], v[50:53]
	v_mfma_f32_16x16x32_bf16 v[38:41], v[146:149], v[176:179], v[38:41]
	v_mfma_f32_16x16x32_bf16 v[34:37], v[154:157], v[176:179], v[34:37]
	v_mfma_f32_16x16x32_bf16 v[22:25], v[146:149], v[184:187], v[22:25]
	v_mfma_f32_16x16x32_bf16 v[18:21], v[154:157], v[184:187], v[18:21]
	v_mfma_f32_16x16x32_bf16 v[6:9], v[146:149], v[192:195], v[6:9]
	v_mfma_f32_16x16x32_bf16 v[2:5], v[154:157], v[192:195], v[2:5]
	v_mfma_f32_16x16x32_bf16 v[54:57], v[150:153], v[172:175], v[54:57]
	v_mfma_f32_16x16x32_bf16 v[50:53], v[164:167], v[172:175], v[50:53]
	v_mfma_f32_16x16x32_bf16 v[38:41], v[150:153], v[180:183], v[38:41]
	v_mfma_f32_16x16x32_bf16 v[34:37], v[164:167], v[180:183], v[34:37]
	v_mfma_f32_16x16x32_bf16 v[22:25], v[150:153], v[188:191], v[22:25]
	v_mfma_f32_16x16x32_bf16 v[18:21], v[164:167], v[188:191], v[18:21]
	v_mfma_f32_16x16x32_bf16 v[6:9], v[150:153], v[200:203], v[6:9]
	v_mfma_f32_16x16x32_bf16 v[2:5], v[164:167], v[200:203], v[2:5]
	s_barrier
	s_setprio 0
	s_mov_b32 m0, s44
	s_nop 0
	buffer_load_dwordx4 v0, s[20:23], s62 offen lds
	s_mov_b32 m0, s36
	s_nop 0
	buffer_load_dwordx4 v159, s[20:23], s62 offen lds
	v_add_u32_e32 v142, 0x18000, v161
	v_add_u32_e32 v163, 0x1c000, v161
	ds_read_b128 v[130:133], v142
	ds_read_b128 v[134:137], v142 offset:1024
	ds_read_b128 v[138:141], v142 offset:2048
	ds_read_b128 v[142:145], v142 offset:3072
	ds_read_b128 v[146:149], v163
	ds_read_b128 v[150:153], v163 offset:1024
	ds_read_b128 v[154:157], v163 offset:2048
	ds_read_b128 v[164:167], v163 offset:3072
	s_add_i32 s62, s62, 0x40000
	s_mov_b32 m0, s37
	ds_read_b128 v[168:171], v162 offset:32768
	ds_read_b128 v[172:175], v162 offset:33792
	ds_read_b128 v[176:179], v162 offset:34816
	ds_read_b128 v[180:183], v162 offset:35840
	ds_read_b128 v[184:187], v162 offset:36864
	ds_read_b128 v[188:191], v162 offset:37888
	ds_read_b128 v[192:195], v162 offset:38912
	ds_read_b128 v[200:203], v162 offset:39936
	buffer_load_dwordx4 v0, s[20:23], s62 offen lds
	s_mov_b32 m0, s38
	s_nop 0
	buffer_load_dwordx4 v159, s[20:23], s62 offen lds
	s_waitcnt vmcnt(8)
	s_waitcnt lgkmcnt(0)
	s_setprio 1
	s_barrier
	v_mfma_f32_16x16x32_bf16 v[126:129], v[130:133], v[168:171], v[126:129]
	v_mfma_f32_16x16x32_bf16 v[122:125], v[138:141], v[168:171], v[122:125]
	v_mfma_f32_16x16x32_bf16 v[110:113], v[130:133], v[176:179], v[110:113]
	v_mfma_f32_16x16x32_bf16 v[106:109], v[138:141], v[176:179], v[106:109]
	v_mfma_f32_16x16x32_bf16 v[94:97], v[130:133], v[184:187], v[94:97]
	v_mfma_f32_16x16x32_bf16 v[90:93], v[138:141], v[184:187], v[90:93]
	v_mfma_f32_16x16x32_bf16 v[78:81], v[130:133], v[192:195], v[78:81]
	v_mfma_f32_16x16x32_bf16 v[74:77], v[138:141], v[192:195], v[74:77]
	v_mfma_f32_16x16x32_bf16 v[126:129], v[134:137], v[172:175], v[126:129]
	v_mfma_f32_16x16x32_bf16 v[122:125], v[142:145], v[172:175], v[122:125]
	v_mfma_f32_16x16x32_bf16 v[110:113], v[134:137], v[180:183], v[110:113]
	v_mfma_f32_16x16x32_bf16 v[106:109], v[142:145], v[180:183], v[106:109]
	v_mfma_f32_16x16x32_bf16 v[94:97], v[134:137], v[188:191], v[94:97]
	v_mfma_f32_16x16x32_bf16 v[90:93], v[142:145], v[188:191], v[90:93]
	v_mfma_f32_16x16x32_bf16 v[78:81], v[134:137], v[200:203], v[78:81]
	v_mfma_f32_16x16x32_bf16 v[74:77], v[142:145], v[200:203], v[74:77]
	v_mfma_f32_16x16x32_bf16 v[118:121], v[146:149], v[168:171], v[118:121]
	v_mfma_f32_16x16x32_bf16 v[114:117], v[154:157], v[168:171], v[114:117]
	v_mfma_f32_16x16x32_bf16 v[102:105], v[146:149], v[176:179], v[102:105]
	v_mfma_f32_16x16x32_bf16 v[98:101], v[154:157], v[176:179], v[98:101]
	v_mfma_f32_16x16x32_bf16 v[86:89], v[146:149], v[184:187], v[86:89]
	v_mfma_f32_16x16x32_bf16 v[82:85], v[154:157], v[184:187], v[82:85]
	v_mfma_f32_16x16x32_bf16 v[70:73], v[146:149], v[192:195], v[70:73]
	v_mfma_f32_16x16x32_bf16 v[66:69], v[154:157], v[192:195], v[66:69]
	v_mfma_f32_16x16x32_bf16 v[118:121], v[150:153], v[172:175], v[118:121]
	v_mfma_f32_16x16x32_bf16 v[114:117], v[164:167], v[172:175], v[114:117]
	v_mfma_f32_16x16x32_bf16 v[102:105], v[150:153], v[180:183], v[102:105]
	v_mfma_f32_16x16x32_bf16 v[98:101], v[164:167], v[180:183], v[98:101]
	v_mfma_f32_16x16x32_bf16 v[86:89], v[150:153], v[188:191], v[86:89]
	v_mfma_f32_16x16x32_bf16 v[82:85], v[164:167], v[188:191], v[82:85]
	v_mfma_f32_16x16x32_bf16 v[70:73], v[150:153], v[200:203], v[70:73]
	v_mfma_f32_16x16x32_bf16 v[66:69], v[164:167], v[200:203], v[66:69]
	s_barrier
	s_setprio 0
	s_mov_b32 m0, s39
	s_or_b32 s62, s60, 0x80
	ds_read_b128 v[168:171], v162 offset:49152
	ds_read_b128 v[172:175], v162 offset:50176
	ds_read_b128 v[176:179], v162 offset:51200
	ds_read_b128 v[180:183], v162 offset:52224
	ds_read_b128 v[184:187], v162 offset:53248
	ds_read_b128 v[188:191], v162 offset:54272
	ds_read_b128 v[192:195], v162 offset:55296
	ds_read_b128 v[200:203], v162 offset:56320
	buffer_load_dwordx4 v158, s[16:19], s62 offen lds
	s_mov_b32 m0, s40
	s_add_i32 s60, s60, 0x40080
	buffer_load_dwordx4 v160, s[16:19], s62 offen lds
	s_mov_b32 m0, s43
	s_nop 0
	buffer_load_dwordx4 v158, s[16:19], s60 offen lds
	s_mov_b32 m0, s42
	s_nop 0
	buffer_load_dwordx4 v160, s[16:19], s60 offen lds
	s_add_i32 s59, s59, 2
	s_addk_i32 s2, 0x100
	s_addk_i32 s3, 0x100
	s_cmp_gt_u32 s59, 13
	s_waitcnt vmcnt(6)
	s_waitcnt lgkmcnt(0)
	s_cbranch_scc0 .LBB0_1235
	s_setprio 1
	s_barrier
	v_mfma_f32_16x16x32_bf16 v[62:65], v[130:133], v[168:171], v[62:65]
	v_mfma_f32_16x16x32_bf16 v[58:61], v[138:141], v[168:171], v[58:61]
	v_mfma_f32_16x16x32_bf16 v[46:49], v[130:133], v[176:179], v[46:49]
	v_mfma_f32_16x16x32_bf16 v[42:45], v[138:141], v[176:179], v[42:45]
	v_mfma_f32_16x16x32_bf16 v[30:33], v[130:133], v[184:187], v[30:33]
	v_mfma_f32_16x16x32_bf16 v[26:29], v[138:141], v[184:187], v[26:29]
	v_mfma_f32_16x16x32_bf16 v[14:17], v[130:133], v[192:195], v[14:17]
	v_mfma_f32_16x16x32_bf16 v[10:13], v[138:141], v[192:195], v[10:13]
	v_mfma_f32_16x16x32_bf16 v[62:65], v[134:137], v[172:175], v[62:65]
	v_mfma_f32_16x16x32_bf16 v[58:61], v[142:145], v[172:175], v[58:61]
	v_mfma_f32_16x16x32_bf16 v[46:49], v[134:137], v[180:183], v[46:49]
	v_mfma_f32_16x16x32_bf16 v[42:45], v[142:145], v[180:183], v[42:45]
	v_mfma_f32_16x16x32_bf16 v[30:33], v[134:137], v[188:191], v[30:33]
	v_mfma_f32_16x16x32_bf16 v[26:29], v[142:145], v[188:191], v[26:29]
	v_mfma_f32_16x16x32_bf16 v[14:17], v[134:137], v[200:203], v[14:17]
	v_mfma_f32_16x16x32_bf16 v[10:13], v[142:145], v[200:203], v[10:13]
	v_mfma_f32_16x16x32_bf16 v[54:57], v[146:149], v[168:171], v[54:57]
	v_mfma_f32_16x16x32_bf16 v[50:53], v[154:157], v[168:171], v[50:53]
	v_mfma_f32_16x16x32_bf16 v[38:41], v[146:149], v[176:179], v[38:41]
	v_mfma_f32_16x16x32_bf16 v[34:37], v[154:157], v[176:179], v[34:37]
	v_mfma_f32_16x16x32_bf16 v[22:25], v[146:149], v[184:187], v[22:25]
	v_mfma_f32_16x16x32_bf16 v[18:21], v[154:157], v[184:187], v[18:21]
	v_mfma_f32_16x16x32_bf16 v[6:9], v[146:149], v[192:195], v[6:9]
	v_mfma_f32_16x16x32_bf16 v[2:5], v[154:157], v[192:195], v[2:5]
	v_mfma_f32_16x16x32_bf16 v[54:57], v[150:153], v[172:175], v[54:57]
	v_mfma_f32_16x16x32_bf16 v[50:53], v[164:167], v[172:175], v[50:53]
	v_mfma_f32_16x16x32_bf16 v[38:41], v[150:153], v[180:183], v[38:41]
	v_mfma_f32_16x16x32_bf16 v[34:37], v[164:167], v[180:183], v[34:37]
	v_mfma_f32_16x16x32_bf16 v[22:25], v[150:153], v[188:191], v[22:25]
	v_mfma_f32_16x16x32_bf16 v[18:21], v[164:167], v[188:191], v[18:21]
	v_mfma_f32_16x16x32_bf16 v[6:9], v[150:153], v[200:203], v[6:9]
	v_mfma_f32_16x16x32_bf16 v[2:5], v[164:167], v[200:203], v[2:5]
	s_barrier
	s_setprio 0
	s_mov_b32 m0, s41
	s_nop 0
	buffer_load_dwordx4 v0, s[20:23], s61 offen lds
	s_mov_b32 m0, s33
	s_nop 0
	buffer_load_dwordx4 v159, s[20:23], s61 offen lds
	v_readlane_b32 s2, v251, 45
	v_readlane_b32 s3, v251, 46
	s_and_b64 vcc, exec, s[2:3]
	s_cbranch_vccz .LBB0_1238
	s_barrier

; #define PG8_WAIT_V(n) asm volatile("s_waitcnt vmcnt(" #n ")" ::: "memory")
; template <class Epi, bool ALIGN_EPI, bool SP2, class Hook>
; __device__ __forceinline__ void gemm_phase(LAS unsigned char* lds, const Gemm g, const StaticOrder& S, const Epi& E, Acc& acc, const bool fresh, const Hook& H, const int wave_id) {
;     ...
;         for (int t = t0; t < nt; t += 2) {
;             const bool last = (t == nt - 2);
;             const Src a1 = cA + (size_t)(t + 1) * kstep;
;             const Src a2 = last ? nA : cA + (size_t)(t + 2) * kstep, b2 = last ? nB : cB + (size_t)(t + 2) * kstep;
;             const Src a3 = a2 + kstep, b3 = b2 + kstep;
;             if (last && has_next) H(nxt);
;             if constexpr (SP2) {
;             PG8_TRIP_SP2(PG8_WAIT_V(8));
.LBB0_1460:
	s_add_i32 s54, s16, -2
	s_lshl_b32 s16, s16, 7
	s_add_i32 s18, s18, s16
	s_add_i32 s16, s17, s16
	s_add_i32 s55, s18, 0x40080
	s_add_i32 s56, s16, 0x100
	s_branch .Lrot_in_8
.LBB0_1461:
	s_setprio 1
	s_barrier
	v_mfma_f32_16x16x32_bf16 v[60:63], v[142:145], v[174:177], v[60:63]
	v_mfma_f32_16x16x32_bf16 v[52:55], v[150:153], v[174:177], v[52:55]
	v_mfma_f32_16x16x32_bf16 v[44:47], v[142:145], v[182:185], v[44:47]
	v_mfma_f32_16x16x32_bf16 v[36:39], v[150:153], v[182:185], v[36:39]
	v_mfma_f32_16x16x32_bf16 v[28:31], v[142:145], v[190:193], v[28:31]
	v_mfma_f32_16x16x32_bf16 v[20:23], v[150:153], v[190:193], v[20:23]
	v_mfma_f32_16x16x32_bf16 v[12:15], v[142:145], v[200:203], v[12:15]
	v_mfma_f32_16x16x32_bf16 v[2:5], v[150:153], v[200:203], v[2:5]
	v_mfma_f32_16x16x32_bf16 v[60:63], v[146:149], v[178:181], v[60:63]
	v_mfma_f32_16x16x32_bf16 v[52:55], v[154:157], v[178:181], v[52:55]
	v_mfma_f32_16x16x32_bf16 v[44:47], v[146:149], v[186:189], v[44:47]
	v_mfma_f32_16x16x32_bf16 v[36:39], v[154:157], v[186:189], v[36:39]
	v_mfma_f32_16x16x32_bf16 v[28:31], v[146:149], v[194:197], v[28:31]
	v_mfma_f32_16x16x32_bf16 v[20:23], v[154:157], v[194:197], v[20:23]
	v_mfma_f32_16x16x32_bf16 v[12:15], v[146:149], v[204:207], v[12:15]
	v_mfma_f32_16x16x32_bf16 v[4:7], v[154:157], v[204:207], v[2:5]
	v_mfma_f32_16x16x32_bf16 v[72:75], v[158:161], v[174:177], v[72:75]
	v_mfma_f32_16x16x32_bf16 v[56:59], v[166:169], v[174:177], v[56:59]
	v_mfma_f32_16x16x32_bf16 v[48:51], v[158:161], v[182:185], v[48:51]
	v_mfma_f32_16x16x32_bf16 v[40:43], v[166:169], v[182:185], v[40:43]
	v_mfma_f32_16x16x32_bf16 v[32:35], v[158:161], v[190:193], v[32:35]
	v_mfma_f32_16x16x32_bf16 v[24:27], v[166:169], v[190:193], v[24:27]
	v_mfma_f32_16x16x32_bf16 v[16:19], v[158:161], v[200:203], v[16:19]
	v_mfma_f32_16x16x32_bf16 v[8:11], v[166:169], v[200:203], v[8:11]
	v_mfma_f32_16x16x32_bf16 v[72:75], v[162:165], v[178:181], v[72:75]
	v_mfma_f32_16x16x32_bf16 v[56:59], v[170:173], v[178:181], v[56:59]
	v_mfma_f32_16x16x32_bf16 v[48:51], v[162:165], v[186:189], v[48:51]
	v_mfma_f32_16x16x32_bf16 v[40:43], v[170:173], v[186:189], v[40:43]
	v_mfma_f32_16x16x32_bf16 v[32:35], v[162:165], v[194:197], v[32:35]
	v_mfma_f32_16x16x32_bf16 v[24:27], v[170:173], v[194:197], v[24:27]
	v_mfma_f32_16x16x32_bf16 v[16:19], v[162:165], v[204:207], v[16:19]
	v_mfma_f32_16x16x32_bf16 v[8:11], v[170:173], v[204:207], v[8:11]
	s_barrier
	s_setprio 0
.Lrot_in_8:
	s_add_i32 s100, s55, 0xfffc0000
	v_add_u32_e32 v138, 0x10000, v136
	v_add_u32_e32 v139, 0x14000, v136
	ds_read_b128 v[140:143], v138
	ds_read_b128 v[144:147], v138 offset:1024
	ds_read_b128 v[148:151], v138 offset:2048
	ds_read_b128 v[152:155], v138 offset:3072
	ds_read_b128 v[156:159], v139
	ds_read_b128 v[160:163], v139 offset:1024
	ds_read_b128 v[164:167], v139 offset:2048
	ds_read_b128 v[168:171], v139 offset:3072
	s_mov_b32 m0, s41
	s_nop 0
	buffer_load_dwordx4 v132, s[12:15], s100 offen lds
	s_mov_b32 m0, s33
	s_nop 0
	buffer_load_dwordx4 v134, s[12:15], s100 offen lds
	s_mov_b32 m0, s45
	ds_read_b128 v[172:175], v137
	ds_read_b128 v[176:179], v137 offset:1024
	ds_read_b128 v[180:183], v137 offset:2048
	ds_read_b128 v[184:187], v137 offset:3072
	ds_read_b128 v[188:191], v137 offset:4096
	ds_read_b128 v[192:195], v137 offset:5120
	ds_read_b128 v[200:203], v137 offset:6144
	ds_read_b128 v[204:207], v137 offset:7168
	buffer_load_dwordx4 v132, s[12:15], s55 offen lds
	s_mov_b32 m0, s46
	s_nop 0
	buffer_load_dwordx4 v134, s[12:15], s55 offen lds
	s_waitcnt vmcnt(8)
	s_waitcnt lgkmcnt(0)
	s_setprio 1
	s_barrier
	v_mfma_f32_16x16x32_bf16 v[124:127], v[140:143], v[172:175], v[124:127]
	v_mfma_f32_16x16x32_bf16 v[116:119], v[148:151], v[172:175], v[116:119]
	v_mfma_f32_16x16x32_bf16 v[108:111], v[140:143], v[180:183], v[108:111]
	v_mfma_f32_16x16x32_bf16 v[100:103], v[148:151], v[180:183], v[100:103]
	v_mfma_f32_16x16x32_bf16 v[92:95], v[140:143], v[188:191], v[92:95]
	v_mfma_f32_16x16x32_bf16 v[84:87], v[148:151], v[188:191], v[84:87]
	v_mfma_f32_16x16x32_bf16 v[76:79], v[140:143], v[200:203], v[76:79]
	v_mfma_f32_16x16x32_bf16 v[64:67], v[148:151], v[200:203], v[64:67]
	v_mfma_f32_16x16x32_bf16 v[124:127], v[144:147], v[176:179], v[124:127]
	v_mfma_f32_16x16x32_bf16 v[116:119], v[152:155], v[176:179], v[116:119]
	v_mfma_f32_16x16x32_bf16 v[108:111], v[144:147], v[184:187], v[108:111]
	v_mfma_f32_16x16x32_bf16 v[100:103], v[152:155], v[184:187], v[100:103]
	v_mfma_f32_16x16x32_bf16 v[92:95], v[144:147], v[192:195], v[92:95]
	v_mfma_f32_16x16x32_bf16 v[84:87], v[152:155], v[192:195], v[84:87]
	v_mfma_f32_16x16x32_bf16 v[76:79], v[144:147], v[204:207], v[76:79]
	v_mfma_f32_16x16x32_bf16 v[64:67], v[152:155], v[204:207], v[64:67]
	v_mfma_f32_16x16x32_bf16 v[128:131], v[156:159], v[172:175], v[128:131]
	v_mfma_f32_16x16x32_bf16 v[120:123], v[164:167], v[172:175], v[120:123]
	v_mfma_f32_16x16x32_bf16 v[112:115], v[156:159], v[180:183], v[112:115]
	v_mfma_f32_16x16x32_bf16 v[104:107], v[164:167], v[180:183], v[104:107]
	v_mfma_f32_16x16x32_bf16 v[96:99], v[156:159], v[188:191], v[96:99]
	v_mfma_f32_16x16x32_bf16 v[88:91], v[164:167], v[188:191], v[88:91]
	v_mfma_f32_16x16x32_bf16 v[80:83], v[156:159], v[200:203], v[80:83]
	v_mfma_f32_16x16x32_bf16 v[68:71], v[164:167], v[200:203], v[68:71]
	v_mfma_f32_16x16x32_bf16 v[128:131], v[160:163], v[176:179], v[128:131]
	v_mfma_f32_16x16x32_bf16 v[120:123], v[168:171], v[176:179], v[120:123]
	v_mfma_f32_16x16x32_bf16 v[112:115], v[160:163], v[184:187], v[112:115]
	v_mfma_f32_16x16x32_bf16 v[104:107], v[168:171], v[184:187], v[104:107]
	v_mfma_f32_16x16x32_bf16 v[96:99], v[160:163], v[192:195], v[96:99]
	v_mfma_f32_16x16x32_bf16 v[88:91], v[168:171], v[192:195], v[88:91]
	v_mfma_f32_16x16x32_bf16 v[80:83], v[160:163], v[204:207], v[80:83]
	v_mfma_f32_16x16x32_bf16 v[68:71], v[168:171], v[204:207], v[68:71]
	s_barrier
; template <class Epi, bool ALIGN_EPI, bool SP2, class Hook>
; __device__ __forceinline__ void gemm_phase(LAS unsigned char* lds, const Gemm g, const StaticOrder& S, const Epi& E, Acc& acc, const bool fresh, const Hook& H, const int wave_id) {
;     ...
;             const Src a1 = cA + (size_t)(t + 1) * kstep;
;             const Src a2 = last ? nA : cA + (size_t)(t + 2) * kstep, b2 = last ? nB : cB + (size_t)(t + 2) * kstep;
;             const Src a3 = a2 + kstep, b3 = b2 + kstep;
	s_setprio 0
	s_add_i32 s16, s55, 0xfffc0080
	s_cmp_eq_u32 s54, 12
	s_cselect_b32 s59, s50, s16
	s_cselect_b32 s17, s9, s77
	s_cselect_b32 s16, s8, s76
	s_cselect_b32 s19, s11, s29
	s_cselect_b32 s18, s10, s28
	s_cselect_b32 s57, s51, s56
	s_cselect_b32 s20, s4, s12
	s_cselect_b32 s21, s5, s13
	s_cselect_b32 s22, s6, s14
	s_cselect_b32 s23, s7, s15
	s_or_b32 s58, s59, 0x80
	s_mov_b32 m0, s92
	ds_read_b128 v[172:175], v137 offset:16384
	ds_read_b128 v[176:179], v137 offset:17408
	ds_read_b128 v[180:183], v137 offset:18432
	ds_read_b128 v[184:187], v137 offset:19456
	ds_read_b128 v[188:191], v137 offset:20480
	ds_read_b128 v[192:195], v137 offset:21504
	ds_read_b128 v[200:203], v137 offset:22528
	ds_read_b128 v[204:207], v137 offset:23552
	buffer_load_dwordx4 v133, s[16:19], s57 offen lds
	s_mov_b32 m0, s93
	s_add_i32 s60, s57, 0x40000
	buffer_load_dwordx4 v135, s[16:19], s57 offen lds
	s_mov_b32 m0, s94
	s_nop 0
	buffer_load_dwordx4 v133, s[16:19], s60 offen lds
	s_mov_b32 m0, s95
	s_nop 0
	buffer_load_dwordx4 v135, s[16:19], s60 offen lds
	s_waitcnt vmcnt(6)
	s_waitcnt lgkmcnt(0)
	s_setprio 1
	s_barrier
	v_mfma_f32_16x16x32_bf16 v[60:63], v[140:143], v[172:175], v[60:63]
	v_mfma_f32_16x16x32_bf16 v[52:55], v[148:151], v[172:175], v[52:55]
	v_mfma_f32_16x16x32_bf16 v[44:47], v[140:143], v[180:183], v[44:47]
	v_mfma_f32_16x16x32_bf16 v[36:39], v[148:151], v[180:183], v[36:39]
	v_mfma_f32_16x16x32_bf16 v[28:31], v[140:143], v[188:191], v[28:31]
	v_mfma_f32_16x16x32_bf16 v[20:23], v[148:151], v[188:191], v[20:23]
	v_mfma_f32_16x16x32_bf16 v[12:15], v[140:143], v[200:203], v[12:15]
	v_mfma_f32_16x16x32_bf16 v[2:5], v[148:151], v[200:203], v[4:7]
	v_mfma_f32_16x16x32_bf16 v[60:63], v[144:147], v[176:179], v[60:63]
	v_mfma_f32_16x16x32_bf16 v[52:55], v[152:155], v[176:179], v[52:55]
	v_mfma_f32_16x16x32_bf16 v[44:47], v[144:147], v[184:187], v[44:47]
	v_mfma_f32_16x16x32_bf16 v[36:39], v[152:155], v[184:187], v[36:39]
	v_mfma_f32_16x16x32_bf16 v[28:31], v[144:147], v[192:195], v[28:31]
	v_mfma_f32_16x16x32_bf16 v[20:23], v[152:155], v[192:195], v[20:23]
	v_mfma_f32_16x16x32_bf16 v[12:15], v[144:147], v[204:207], v[12:15]
	v_mfma_f32_16x16x32_bf16 v[2:5], v[152:155], v[204:207], v[2:5]
	v_mfma_f32_16x16x32_bf16 v[72:75], v[156:159], v[172:175], v[72:75]
	v_mfma_f32_16x16x32_bf16 v[56:59], v[164:167], v[172:175], v[56:59]
	v_mfma_f32_16x16x32_bf16 v[48:51], v[156:159], v[180:183], v[48:51]
	v_mfma_f32_16x16x32_bf16 v[40:43], v[164:167], v[180:183], v[40:43]
	v_mfma_f32_16x16x32_bf16 v[32:35], v[156:159], v[188:191], v[32:35]
	v_mfma_f32_16x16x32_bf16 v[24:27], v[164:167], v[188:191], v[24:27]
	v_mfma_f32_16x16x32_bf16 v[16:19], v[156:159], v[200:203], v[16:19]
	v_mfma_f32_16x16x32_bf16 v[6:9], v[164:167], v[200:203], v[8:11]
	v_mfma_f32_16x16x32_bf16 v[72:75], v[160:163], v[176:179], v[72:75]
	v_mfma_f32_16x16x32_bf16 v[56:59], v[168:171], v[176:179], v[56:59]
	v_mfma_f32_16x16x32_bf16 v[48:51], v[160:163], v[184:187], v[48:51]
	v_mfma_f32_16x16x32_bf16 v[40:43], v[168:171], v[184:187], v[40:43]
	v_mfma_f32_16x16x32_bf16 v[32:35], v[160:163], v[192:195], v[32:35]
	v_mfma_f32_16x16x32_bf16 v[24:27], v[168:171], v[192:195], v[24:27]
	v_mfma_f32_16x16x32_bf16 v[16:19], v[160:163], v[204:207], v[16:19]
	v_mfma_f32_16x16x32_bf16 v[8:11], v[168:171], v[204:207], v[6:9]
	s_barrier
	s_setprio 0
	s_mov_b32 m0, s44
	s_nop 0
	buffer_load_dwordx4 v132, s[20:23], s59 offen lds
	s_mov_b32 m0, s36
	s_nop 0
	buffer_load_dwordx4 v134, s[20:23], s59 offen lds
	v_add_u32_e32 v140, 0x18000, v136
	v_add_u32_e32 v141, 0x1c000, v136
	ds_read_b128 v[142:145], v140
	ds_read_b128 v[146:149], v140 offset:1024
	ds_read_b128 v[150:153], v140 offset:2048
	ds_read_b128 v[154:157], v140 offset:3072
	ds_read_b128 v[158:161], v141
	ds_read_b128 v[162:165], v141 offset:1024
	ds_read_b128 v[166:169], v141 offset:2048
	ds_read_b128 v[170:173], v141 offset:3072
	s_add_i32 s59, s59, 0x40000
	s_mov_b32 m0, s37
	ds_read_b128 v[174:177], v137 offset:32768
	ds_read_b128 v[178:181], v137 offset:33792
	ds_read_b128 v[182:185], v137 offset:34816
	ds_read_b128 v[186:189], v137 offset:35840
	ds_read_b128 v[190:193], v137 offset:36864
	ds_read_b128 v[194:197], v137 offset:37888
	ds_read_b128 v[200:203], v137 offset:38912
	ds_read_b128 v[204:207], v137 offset:39936
	buffer_load_dwordx4 v132, s[20:23], s59 offen lds
	s_mov_b32 m0, s38
	s_nop 0
	buffer_load_dwordx4 v134, s[20:23], s59 offen lds
	s_waitcnt vmcnt(8)
	s_waitcnt lgkmcnt(0)
	s_setprio 1
	s_barrier
; template <class Epi, bool ALIGN_EPI, bool SP2, class Hook>
; __device__ __forceinline__ void gemm_phase(LAS unsigned char* lds, const Gemm g, const StaticOrder& S, const Epi& E, Acc& acc, const bool fresh, const Hook& H, const int wave_id) {
;     ...
;         for (int t = t0; t < nt; t += 2) {
;             const bool last = (t == nt - 2);
	v_mfma_f32_16x16x32_bf16 v[124:127], v[142:145], v[174:177], v[124:127]
	v_mfma_f32_16x16x32_bf16 v[116:119], v[150:153], v[174:177], v[116:119]
	v_mfma_f32_16x16x32_bf16 v[108:111], v[142:145], v[182:185], v[108:111]
	v_mfma_f32_16x16x32_bf16 v[100:103], v[150:153], v[182:185], v[100:103]
	v_mfma_f32_16x16x32_bf16 v[92:95], v[142:145], v[190:193], v[92:95]
	v_mfma_f32_16x16x32_bf16 v[84:87], v[150:153], v[190:193], v[84:87]
	v_mfma_f32_16x16x32_bf16 v[76:79], v[142:145], v[200:203], v[76:79]
	v_mfma_f32_16x16x32_bf16 v[64:67], v[150:153], v[200:203], v[64:67]
	v_mfma_f32_16x16x32_bf16 v[124:127], v[146:149], v[178:181], v[124:127]
	v_mfma_f32_16x16x32_bf16 v[116:119], v[154:157], v[178:181], v[116:119]
	v_mfma_f32_16x16x32_bf16 v[108:111], v[146:149], v[186:189], v[108:111]
	v_mfma_f32_16x16x32_bf16 v[100:103], v[154:157], v[186:189], v[100:103]
	v_mfma_f32_16x16x32_bf16 v[92:95], v[146:149], v[194:197], v[92:95]
	v_mfma_f32_16x16x32_bf16 v[84:87], v[154:157], v[194:197], v[84:87]
	v_mfma_f32_16x16x32_bf16 v[76:79], v[146:149], v[204:207], v[76:79]
	v_mfma_f32_16x16x32_bf16 v[64:67], v[154:157], v[204:207], v[64:67]
	v_mfma_f32_16x16x32_bf16 v[128:131], v[158:161], v[174:177], v[128:131]
	v_mfma_f32_16x16x32_bf16 v[120:123], v[166:169], v[174:177], v[120:123]
	v_mfma_f32_16x16x32_bf16 v[112:115], v[158:161], v[182:185], v[112:115]
	v_mfma_f32_16x16x32_bf16 v[104:107], v[166:169], v[182:185], v[104:107]
	v_mfma_f32_16x16x32_bf16 v[96:99], v[158:161], v[190:193], v[96:99]
	v_mfma_f32_16x16x32_bf16 v[88:91], v[166:169], v[190:193], v[88:91]
	v_mfma_f32_16x16x32_bf16 v[80:83], v[158:161], v[200:203], v[80:83]
	v_mfma_f32_16x16x32_bf16 v[68:71], v[166:169], v[200:203], v[68:71]
	v_mfma_f32_16x16x32_bf16 v[128:131], v[162:165], v[178:181], v[128:131]
	v_mfma_f32_16x16x32_bf16 v[120:123], v[170:173], v[178:181], v[120:123]
	v_mfma_f32_16x16x32_bf16 v[112:115], v[162:165], v[186:189], v[112:115]
	v_mfma_f32_16x16x32_bf16 v[104:107], v[170:173], v[186:189], v[104:107]
	v_mfma_f32_16x16x32_bf16 v[96:99], v[162:165], v[194:197], v[96:99]
	v_mfma_f32_16x16x32_bf16 v[88:91], v[170:173], v[194:197], v[88:91]
	v_mfma_f32_16x16x32_bf16 v[80:83], v[162:165], v[204:207], v[80:83]
	v_mfma_f32_16x16x32_bf16 v[68:71], v[170:173], v[204:207], v[68:71]
	s_barrier
	s_setprio 0
	s_mov_b32 m0, s39
	s_or_b32 s59, s57, 0x80
	ds_read_b128 v[174:177], v137 offset:49152
	ds_read_b128 v[178:181], v137 offset:50176
	ds_read_b128 v[182:185], v137 offset:51200
	ds_read_b128 v[186:189], v137 offset:52224
	ds_read_b128 v[190:193], v137 offset:53248
	ds_read_b128 v[194:197], v137 offset:54272
	ds_read_b128 v[200:203], v137 offset:55296
	ds_read_b128 v[204:207], v137 offset:56320
	buffer_load_dwordx4 v133, s[16:19], s59 offen lds
	s_mov_b32 m0, s40
	s_add_i32 s57, s57, 0x40080
	buffer_load_dwordx4 v135, s[16:19], s59 offen lds
	s_mov_b32 m0, s43
	s_nop 0
	buffer_load_dwordx4 v133, s[16:19], s57 offen lds
	s_mov_b32 m0, s42
	s_nop 0
	buffer_load_dwordx4 v135, s[16:19], s57 offen lds
	s_add_i32 s54, s54, 2
	s_addk_i32 s55, 0x100
	s_addk_i32 s56, 0x100
	s_cmp_gt_u32 s54, 13
	s_waitcnt vmcnt(6)
	s_waitcnt lgkmcnt(0)
	s_cbranch_scc0 .LBB0_1461
	s_setprio 1
	s_barrier
	v_mfma_f32_16x16x32_bf16 v[60:63], v[142:145], v[174:177], v[60:63]
	v_mfma_f32_16x16x32_bf16 v[52:55], v[150:153], v[174:177], v[52:55]
	v_mfma_f32_16x16x32_bf16 v[44:47], v[142:145], v[182:185], v[44:47]
	v_mfma_f32_16x16x32_bf16 v[36:39], v[150:153], v[182:185], v[36:39]
	v_mfma_f32_16x16x32_bf16 v[28:31], v[142:145], v[190:193], v[28:31]
	v_mfma_f32_16x16x32_bf16 v[20:23], v[150:153], v[190:193], v[20:23]
	v_mfma_f32_16x16x32_bf16 v[12:15], v[142:145], v[200:203], v[12:15]
	v_mfma_f32_16x16x32_bf16 v[2:5], v[150:153], v[200:203], v[2:5]
	v_mfma_f32_16x16x32_bf16 v[60:63], v[146:149], v[178:181], v[60:63]
	v_mfma_f32_16x16x32_bf16 v[52:55], v[154:157], v[178:181], v[52:55]
	v_mfma_f32_16x16x32_bf16 v[44:47], v[146:149], v[186:189], v[44:47]
	v_mfma_f32_16x16x32_bf16 v[36:39], v[154:157], v[186:189], v[36:39]
	v_mfma_f32_16x16x32_bf16 v[28:31], v[146:149], v[194:197], v[28:31]
	v_mfma_f32_16x16x32_bf16 v[20:23], v[154:157], v[194:197], v[20:23]
	v_mfma_f32_16x16x32_bf16 v[12:15], v[146:149], v[204:207], v[12:15]
	v_mfma_f32_16x16x32_bf16 v[4:7], v[154:157], v[204:207], v[2:5]
	v_mfma_f32_16x16x32_bf16 v[72:75], v[158:161], v[174:177], v[72:75]
	v_mfma_f32_16x16x32_bf16 v[56:59], v[166:169], v[174:177], v[56:59]
	v_mfma_f32_16x16x32_bf16 v[48:51], v[158:161], v[182:185], v[48:51]
	v_mfma_f32_16x16x32_bf16 v[40:43], v[166:169], v[182:185], v[40:43]
	v_mfma_f32_16x16x32_bf16 v[32:35], v[158:161], v[190:193], v[32:35]
	v_mfma_f32_16x16x32_bf16 v[24:27], v[166:169], v[190:193], v[24:27]
	v_mfma_f32_16x16x32_bf16 v[16:19], v[158:161], v[200:203], v[16:19]
	v_mfma_f32_16x16x32_bf16 v[8:11], v[166:169], v[200:203], v[8:11]
	v_mfma_f32_16x16x32_bf16 v[72:75], v[162:165], v[178:181], v[72:75]
	v_mfma_f32_16x16x32_bf16 v[56:59], v[170:173], v[178:181], v[56:59]
	v_mfma_f32_16x16x32_bf16 v[48:51], v[162:165], v[186:189], v[48:51]
	v_mfma_f32_16x16x32_bf16 v[40:43], v[170:173], v[186:189], v[40:43]
	v_mfma_f32_16x16x32_bf16 v[32:35], v[162:165], v[194:197], v[32:35]
	v_mfma_f32_16x16x32_bf16 v[24:27], v[170:173], v[194:197], v[24:27]
	v_mfma_f32_16x16x32_bf16 v[16:19], v[162:165], v[204:207], v[16:19]
	v_mfma_f32_16x16x32_bf16 v[8:11], v[170:173], v[204:207], v[8:11]
	s_barrier
	s_setprio 0
	s_mov_b32 m0, s41
	s_nop 0
	buffer_load_dwordx4 v132, s[20:23], s58 offen lds
	s_mov_b32 m0, s33
	s_nop 0
	buffer_load_dwordx4 v134, s[20:23], s58 offen lds
	v_readlane_b32 s12, v251, 45
	v_readlane_b32 s13, v251, 46
	s_and_b64 vcc, exec, s[12:13]
	s_cbranch_vccz .LBB0_1464
	s_barrier

; template <class Epi, bool ALIGN_EPI, bool SP2, class Hook>
; __device__ __forceinline__ void gemm_phase(LAS unsigned char* lds, const Gemm g, const StaticOrder& S, const Epi& E, Acc& acc, const bool fresh, const Hook& H, const int wave_id) {
;     ...
;         for (int t = t0; t < nt; t += 2) {
;             const bool last = (t == nt - 2);
;             const Src a1 = cA + (size_t)(t + 1) * kstep;
;             const Src a2 = last ? nA : cA + (size_t)(t + 2) * kstep, b2 = last ? nB : cB + (size_t)(t + 2) * kstep;
;     ...
;         if (reset) {
; #pragma unroll
;             for (int a = 0; a < 2; ++a)
; #pragma unroll
;                 for (int b = 0; b < 2; ++b)
; #pragma unroll
;                     for (int m = 0; m < 4; ++m)
; #pragma unroll
;                         for (int n = 0; n < 2; ++n) acc[a][b][m][n] = (f32x4){0.f, 0.f, 0.f, 0.f};
;         }
;         cur = nxt; cA = nA; cB = nB; ++ui;
.LBB0_1571:
	v_mov_b32_e32 v2, 0
	s_add_i32 s2, s17, 0xc0080
	s_add_i32 s3, s16, 0x100
	s_mov_b32 s61, -2
	v_mov_b32_e32 v3, v2
	v_mov_b32_e32 v4, v2
	v_mov_b32_e32 v5, v2
	v_mov_b32_e32 v6, v2
	v_mov_b32_e32 v7, v2
	v_mov_b32_e32 v8, v2
	v_mov_b32_e32 v9, v2
	v_mov_b32_e32 v18, v2
	v_mov_b32_e32 v19, v2
	v_mov_b32_e32 v20, v2
	v_mov_b32_e32 v21, v2
	v_mov_b32_e32 v22, v2
	v_mov_b32_e32 v23, v2
	v_mov_b32_e32 v24, v2
	v_mov_b32_e32 v25, v2
	v_mov_b32_e32 v34, v2
	v_mov_b32_e32 v35, v2
	v_mov_b32_e32 v36, v2
	v_mov_b32_e32 v37, v2
	v_mov_b32_e32 v38, v2
	v_mov_b32_e32 v39, v2
	v_mov_b32_e32 v40, v2
	v_mov_b32_e32 v41, v2
	v_mov_b32_e32 v50, v2
	v_mov_b32_e32 v51, v2
	v_mov_b32_e32 v52, v2
	v_mov_b32_e32 v53, v2
	v_mov_b32_e32 v54, v2
	v_mov_b32_e32 v55, v2
	v_mov_b32_e32 v56, v2
	v_mov_b32_e32 v57, v2
	v_mov_b32_e32 v10, v2
	v_mov_b32_e32 v11, v2
	v_mov_b32_e32 v12, v2
	v_mov_b32_e32 v13, v2
	v_mov_b32_e32 v14, v2
	v_mov_b32_e32 v15, v2
	v_mov_b32_e32 v16, v2
	v_mov_b32_e32 v17, v2
	v_mov_b32_e32 v26, v2
	v_mov_b32_e32 v27, v2
	v_mov_b32_e32 v28, v2
	v_mov_b32_e32 v29, v2
	v_mov_b32_e32 v30, v2
	v_mov_b32_e32 v31, v2
	v_mov_b32_e32 v32, v2
	v_mov_b32_e32 v33, v2
	v_mov_b32_e32 v42, v2
	v_mov_b32_e32 v43, v2
	v_mov_b32_e32 v44, v2
	v_mov_b32_e32 v45, v2
	v_mov_b32_e32 v46, v2
	v_mov_b32_e32 v47, v2
	v_mov_b32_e32 v48, v2
	v_mov_b32_e32 v49, v2
	v_mov_b32_e32 v58, v2
	v_mov_b32_e32 v59, v2
	v_mov_b32_e32 v60, v2
	v_mov_b32_e32 v61, v2
	v_mov_b32_e32 v62, v2
	v_mov_b32_e32 v63, v2
	v_mov_b32_e32 v64, v2
	v_mov_b32_e32 v65, v2
	v_mov_b32_e32 v66, v2
	v_mov_b32_e32 v67, v2
	v_mov_b32_e32 v68, v2
	v_mov_b32_e32 v69, v2
	v_mov_b32_e32 v70, v2
	v_mov_b32_e32 v71, v2
	v_mov_b32_e32 v72, v2
	v_mov_b32_e32 v73, v2
	v_mov_b32_e32 v82, v2
	v_mov_b32_e32 v83, v2
	v_mov_b32_e32 v84, v2
	v_mov_b32_e32 v85, v2
	v_mov_b32_e32 v86, v2
	v_mov_b32_e32 v87, v2
	v_mov_b32_e32 v88, v2
	v_mov_b32_e32 v89, v2
	v_mov_b32_e32 v98, v2
	v_mov_b32_e32 v99, v2
	v_mov_b32_e32 v100, v2
	v_mov_b32_e32 v101, v2
	v_mov_b32_e32 v102, v2
	v_mov_b32_e32 v103, v2
	v_mov_b32_e32 v104, v2
	v_mov_b32_e32 v105, v2
	v_mov_b32_e32 v114, v2
	v_mov_b32_e32 v115, v2
	v_mov_b32_e32 v116, v2
	v_mov_b32_e32 v117, v2
	v_mov_b32_e32 v118, v2
	v_mov_b32_e32 v119, v2
	v_mov_b32_e32 v120, v2
	v_mov_b32_e32 v121, v2
	v_mov_b32_e32 v74, v2
	v_mov_b32_e32 v75, v2
	v_mov_b32_e32 v76, v2
	v_mov_b32_e32 v77, v2
	v_mov_b32_e32 v78, v2
	v_mov_b32_e32 v79, v2
	v_mov_b32_e32 v80, v2
	v_mov_b32_e32 v81, v2
	v_mov_b32_e32 v90, v2
	v_mov_b32_e32 v91, v2
	v_mov_b32_e32 v92, v2
	v_mov_b32_e32 v93, v2
	v_mov_b32_e32 v94, v2
	v_mov_b32_e32 v95, v2
	v_mov_b32_e32 v96, v2
	v_mov_b32_e32 v97, v2
	v_mov_b32_e32 v106, v2
	v_mov_b32_e32 v107, v2
	v_mov_b32_e32 v108, v2
	v_mov_b32_e32 v109, v2
	v_mov_b32_e32 v110, v2
	v_mov_b32_e32 v111, v2
	v_mov_b32_e32 v112, v2
	v_mov_b32_e32 v113, v2
	v_mov_b32_e32 v122, v2
	v_mov_b32_e32 v123, v2
	v_mov_b32_e32 v124, v2
	v_mov_b32_e32 v125, v2
	v_mov_b32_e32 v126, v2
	v_mov_b32_e32 v127, v2
	v_mov_b32_e32 v128, v2
	v_mov_b32_e32 v129, v2
	s_branch .Lrot_in_9

; template <class Epi, bool ALIGN_EPI, bool SP2, class Hook>
; __device__ __forceinline__ void gemm_phase(LAS unsigned char* lds, const Gemm g, const StaticOrder& S, const Epi& E, Acc& acc, const bool fresh, const Hook& H, const int wave_id) {
;     ...
;             const Src a1 = cA + (size_t)(t + 1) * kstep;
;             const Src a2 = last ? nA : cA + (size_t)(t + 2) * kstep, b2 = last ? nB : cB + (size_t)(t + 2) * kstep;
;             const Src a3 = a2 + kstep, b3 = b2 + kstep;
.Lrot_in_9:
	s_add_i32 s100, s2, 0xfff40000
	v_add_u32_e32 v142, 0x10000, v161
	v_add_u32_e32 v163, 0x14000, v161
	ds_read_b128 v[130:133], v142
	ds_read_b128 v[134:137], v142 offset:1024
	ds_read_b128 v[138:141], v142 offset:2048
	ds_read_b128 v[142:145], v142 offset:3072
	ds_read_b128 v[146:149], v163
	ds_read_b128 v[150:153], v163 offset:1024
	ds_read_b128 v[154:157], v163 offset:2048
	ds_read_b128 v[164:167], v163 offset:3072
	s_mov_b32 m0, s41
	s_nop 0
	buffer_load_dwordx4 v0, s[12:15], s100 offen lds
	s_mov_b32 m0, s33
	s_nop 0
	buffer_load_dwordx4 v159, s[12:15], s100 offen lds
	s_mov_b32 m0, s45
	ds_read_b128 v[168:171], v162
	ds_read_b128 v[172:175], v162 offset:1024
	ds_read_b128 v[176:179], v162 offset:2048
	ds_read_b128 v[180:183], v162 offset:3072
	ds_read_b128 v[184:187], v162 offset:4096
	ds_read_b128 v[188:191], v162 offset:5120
	ds_read_b128 v[192:195], v162 offset:6144
	ds_read_b128 v[200:203], v162 offset:7168
	buffer_load_dwordx4 v0, s[12:15], s2 offen lds
	s_mov_b32 m0, s46
	s_nop 0
	buffer_load_dwordx4 v159, s[12:15], s2 offen lds
	s_waitcnt vmcnt(8)
	s_waitcnt lgkmcnt(0)
	s_setprio 1
	s_barrier
	v_mfma_f32_16x16x32_bf16 v[126:129], v[130:133], v[168:171], v[126:129]
	v_mfma_f32_16x16x32_bf16 v[122:125], v[138:141], v[168:171], v[122:125]
	v_mfma_f32_16x16x32_bf16 v[110:113], v[130:133], v[176:179], v[110:113]
	v_mfma_f32_16x16x32_bf16 v[106:109], v[138:141], v[176:179], v[106:109]
	v_mfma_f32_16x16x32_bf16 v[94:97], v[130:133], v[184:187], v[94:97]
	v_mfma_f32_16x16x32_bf16 v[90:93], v[138:141], v[184:187], v[90:93]
	v_mfma_f32_16x16x32_bf16 v[78:81], v[130:133], v[192:195], v[78:81]
	v_mfma_f32_16x16x32_bf16 v[74:77], v[138:141], v[192:195], v[74:77]
	v_mfma_f32_16x16x32_bf16 v[126:129], v[134:137], v[172:175], v[126:129]
	v_mfma_f32_16x16x32_bf16 v[122:125], v[142:145], v[172:175], v[122:125]
	v_mfma_f32_16x16x32_bf16 v[110:113], v[134:137], v[180:183], v[110:113]
	v_mfma_f32_16x16x32_bf16 v[106:109], v[142:145], v[180:183], v[106:109]
	v_mfma_f32_16x16x32_bf16 v[94:97], v[134:137], v[188:191], v[94:97]
	v_mfma_f32_16x16x32_bf16 v[90:93], v[142:145], v[188:191], v[90:93]
	v_mfma_f32_16x16x32_bf16 v[78:81], v[134:137], v[200:203], v[78:81]
	v_mfma_f32_16x16x32_bf16 v[74:77], v[142:145], v[200:203], v[74:77]
	v_mfma_f32_16x16x32_bf16 v[118:121], v[146:149], v[168:171], v[118:121]
	v_mfma_f32_16x16x32_bf16 v[114:117], v[154:157], v[168:171], v[114:117]
	v_mfma_f32_16x16x32_bf16 v[102:105], v[146:149], v[176:179], v[102:105]
	v_mfma_f32_16x16x32_bf16 v[98:101], v[154:157], v[176:179], v[98:101]
	v_mfma_f32_16x16x32_bf16 v[86:89], v[146:149], v[184:187], v[86:89]
	v_mfma_f32_16x16x32_bf16 v[82:85], v[154:157], v[184:187], v[82:85]
	v_mfma_f32_16x16x32_bf16 v[70:73], v[146:149], v[192:195], v[70:73]
	v_mfma_f32_16x16x32_bf16 v[66:69], v[154:157], v[192:195], v[66:69]
	v_mfma_f32_16x16x32_bf16 v[118:121], v[150:153], v[172:175], v[118:121]
	v_mfma_f32_16x16x32_bf16 v[114:117], v[164:167], v[172:175], v[114:117]
	v_mfma_f32_16x16x32_bf16 v[102:105], v[150:153], v[180:183], v[102:105]
	v_mfma_f32_16x16x32_bf16 v[98:101], v[164:167], v[180:183], v[98:101]
	v_mfma_f32_16x16x32_bf16 v[86:89], v[150:153], v[188:191], v[86:89]
	v_mfma_f32_16x16x32_bf16 v[82:85], v[164:167], v[188:191], v[82:85]
	v_mfma_f32_16x16x32_bf16 v[70:73], v[150:153], v[200:203], v[70:73]
	v_mfma_f32_16x16x32_bf16 v[66:69], v[164:167], v[200:203], v[66:69]
	s_barrier
	s_setprio 0
	s_add_i32 s16, s2, 0xfff40080
	s_cmp_eq_u32 s61, 40
	s_cselect_b32 s64, s57, s16
	s_cselect_b32 s17, s35, s9
	s_cselect_b32 s16, s34, s8
	s_cselect_b32 s19, s51, s53
	s_cselect_b32 s18, s50, s52
	s_cselect_b32 s62, s58, s3
	s_cselect_b32 s20, s10, s12
	s_cselect_b32 s21, s11, s13
	s_cselect_b32 s22, s30, s14
	s_cselect_b32 s23, s31, s15
	s_or_b32 s63, s64, 0x80
	s_mov_b32 m0, s92
	ds_read_b128 v[168:171], v162 offset:16384
	ds_read_b128 v[172:175], v162 offset:17408
	ds_read_b128 v[176:179], v162 offset:18432
	ds_read_b128 v[180:183], v162 offset:19456
	ds_read_b128 v[184:187], v162 offset:20480
	ds_read_b128 v[188:191], v162 offset:21504
	ds_read_b128 v[192:195], v162 offset:22528
	ds_read_b128 v[200:203], v162 offset:23552
	buffer_load_dwordx4 v158, s[16:19], s62 offen lds
	s_mov_b32 m0, s93
	s_add_i32 s65, s62, 0xb0000
	buffer_load_dwordx4 v160, s[16:19], s62 offen lds
	s_mov_b32 m0, s94
	s_nop 0
	buffer_load_dwordx4 v158, s[16:19], s65 offen lds
	s_mov_b32 m0, s95
	s_nop 0
	buffer_load_dwordx4 v160, s[16:19], s65 offen lds
	s_waitcnt vmcnt(6)
	s_waitcnt lgkmcnt(0)
	s_setprio 1
	s_barrier
	v_mfma_f32_16x16x32_bf16 v[62:65], v[130:133], v[168:171], v[62:65]
	v_mfma_f32_16x16x32_bf16 v[58:61], v[138:141], v[168:171], v[58:61]
	v_mfma_f32_16x16x32_bf16 v[46:49], v[130:133], v[176:179], v[46:49]
	v_mfma_f32_16x16x32_bf16 v[42:45], v[138:141], v[176:179], v[42:45]
	v_mfma_f32_16x16x32_bf16 v[30:33], v[130:133], v[184:187], v[30:33]
	v_mfma_f32_16x16x32_bf16 v[26:29], v[138:141], v[184:187], v[26:29]
	v_mfma_f32_16x16x32_bf16 v[14:17], v[130:133], v[192:195], v[14:17]
	v_mfma_f32_16x16x32_bf16 v[10:13], v[138:141], v[192:195], v[10:13]
	v_mfma_f32_16x16x32_bf16 v[62:65], v[134:137], v[172:175], v[62:65]
	v_mfma_f32_16x16x32_bf16 v[58:61], v[142:145], v[172:175], v[58:61]
	v_mfma_f32_16x16x32_bf16 v[46:49], v[134:137], v[180:183], v[46:49]
	v_mfma_f32_16x16x32_bf16 v[42:45], v[142:145], v[180:183], v[42:45]
	v_mfma_f32_16x16x32_bf16 v[30:33], v[134:137], v[188:191], v[30:33]
	v_mfma_f32_16x16x32_bf16 v[26:29], v[142:145], v[188:191], v[26:29]
	v_mfma_f32_16x16x32_bf16 v[14:17], v[134:137], v[200:203], v[14:17]
	v_mfma_f32_16x16x32_bf16 v[10:13], v[142:145], v[200:203], v[10:13]
	v_mfma_f32_16x16x32_bf16 v[54:57], v[146:149], v[168:171], v[54:57]
	v_mfma_f32_16x16x32_bf16 v[50:53], v[154:157], v[168:171], v[50:53]
	v_mfma_f32_16x16x32_bf16 v[38:41], v[146:149], v[176:179], v[38:41]
	v_mfma_f32_16x16x32_bf16 v[34:37], v[154:157], v[176:179], v[34:37]
	v_mfma_f32_16x16x32_bf16 v[22:25], v[146:149], v[184:187], v[22:25]
	v_mfma_f32_16x16x32_bf16 v[18:21], v[154:157], v[184:187], v[18:21]
	v_mfma_f32_16x16x32_bf16 v[6:9], v[146:149], v[192:195], v[6:9]
	v_mfma_f32_16x16x32_bf16 v[2:5], v[154:157], v[192:195], v[2:5]
	v_mfma_f32_16x16x32_bf16 v[54:57], v[150:153], v[172:175], v[54:57]
	v_mfma_f32_16x16x32_bf16 v[50:53], v[164:167], v[172:175], v[50:53]
	v_mfma_f32_16x16x32_bf16 v[38:41], v[150:153], v[180:183], v[38:41]
	v_mfma_f32_16x16x32_bf16 v[34:37], v[164:167], v[180:183], v[34:37]
	v_mfma_f32_16x16x32_bf16 v[22:25], v[150:153], v[188:191], v[22:25]
	v_mfma_f32_16x16x32_bf16 v[18:21], v[164:167], v[188:191], v[18:21]
	v_mfma_f32_16x16x32_bf16 v[6:9], v[150:153], v[200:203], v[6:9]
	v_mfma_f32_16x16x32_bf16 v[2:5], v[164:167], v[200:203], v[2:5]
	s_barrier
; template <class Epi, bool ALIGN_EPI, bool SP2, class Hook>
; __device__ __forceinline__ void gemm_phase(LAS unsigned char* lds, const Gemm g, const StaticOrder& S, const Epi& E, Acc& acc, const bool fresh, const Hook& H, const int wave_id) {
;     ...
;         for (int t = t0; t < nt; t += 2) {
;             const bool last = (t == nt - 2);
	s_setprio 0
	s_mov_b32 m0, s44
	s_nop 0
	buffer_load_dwordx4 v0, s[20:23], s64 offen lds
	s_mov_b32 m0, s36
	s_nop 0
	buffer_load_dwordx4 v159, s[20:23], s64 offen lds
	v_add_u32_e32 v142, 0x18000, v161
	v_add_u32_e32 v163, 0x1c000, v161
	ds_read_b128 v[130:133], v142
	ds_read_b128 v[134:137], v142 offset:1024
	ds_read_b128 v[138:141], v142 offset:2048
	ds_read_b128 v[142:145], v142 offset:3072
	ds_read_b128 v[146:149], v163
	ds_read_b128 v[150:153], v163 offset:1024
	ds_read_b128 v[154:157], v163 offset:2048
	ds_read_b128 v[164:167], v163 offset:3072
	s_add_i32 s64, s64, 0xc0000
	s_mov_b32 m0, s37
	ds_read_b128 v[168:171], v162 offset:32768
	ds_read_b128 v[172:175], v162 offset:33792
	ds_read_b128 v[176:179], v162 offset:34816
	ds_read_b128 v[180:183], v162 offset:35840
	ds_read_b128 v[184:187], v162 offset:36864
	ds_read_b128 v[188:191], v162 offset:37888
	ds_read_b128 v[192:195], v162 offset:38912
	ds_read_b128 v[200:203], v162 offset:39936
	buffer_load_dwordx4 v0, s[20:23], s64 offen lds
	s_mov_b32 m0, s38
	s_nop 0
	buffer_load_dwordx4 v159, s[20:23], s64 offen lds
	s_waitcnt vmcnt(8)
	s_waitcnt lgkmcnt(0)
	s_setprio 1
	s_barrier
	v_mfma_f32_16x16x32_bf16 v[126:129], v[130:133], v[168:171], v[126:129]
	v_mfma_f32_16x16x32_bf16 v[122:125], v[138:141], v[168:171], v[122:125]
	v_mfma_f32_16x16x32_bf16 v[110:113], v[130:133], v[176:179], v[110:113]
	v_mfma_f32_16x16x32_bf16 v[106:109], v[138:141], v[176:179], v[106:109]
	v_mfma_f32_16x16x32_bf16 v[94:97], v[130:133], v[184:187], v[94:97]
	v_mfma_f32_16x16x32_bf16 v[90:93], v[138:141], v[184:187], v[90:93]
	v_mfma_f32_16x16x32_bf16 v[78:81], v[130:133], v[192:195], v[78:81]
	v_mfma_f32_16x16x32_bf16 v[74:77], v[138:141], v[192:195], v[74:77]
	v_mfma_f32_16x16x32_bf16 v[126:129], v[134:137], v[172:175], v[126:129]
	v_mfma_f32_16x16x32_bf16 v[122:125], v[142:145], v[172:175], v[122:125]
	v_mfma_f32_16x16x32_bf16 v[110:113], v[134:137], v[180:183], v[110:113]
	v_mfma_f32_16x16x32_bf16 v[106:109], v[142:145], v[180:183], v[106:109]
	v_mfma_f32_16x16x32_bf16 v[94:97], v[134:137], v[188:191], v[94:97]
	v_mfma_f32_16x16x32_bf16 v[90:93], v[142:145], v[188:191], v[90:93]
	v_mfma_f32_16x16x32_bf16 v[78:81], v[134:137], v[200:203], v[78:81]
	v_mfma_f32_16x16x32_bf16 v[74:77], v[142:145], v[200:203], v[74:77]
	v_mfma_f32_16x16x32_bf16 v[118:121], v[146:149], v[168:171], v[118:121]
	v_mfma_f32_16x16x32_bf16 v[114:117], v[154:157], v[168:171], v[114:117]
	v_mfma_f32_16x16x32_bf16 v[102:105], v[146:149], v[176:179], v[102:105]
	v_mfma_f32_16x16x32_bf16 v[98:101], v[154:157], v[176:179], v[98:101]
	v_mfma_f32_16x16x32_bf16 v[86:89], v[146:149], v[184:187], v[86:89]
	v_mfma_f32_16x16x32_bf16 v[82:85], v[154:157], v[184:187], v[82:85]
	v_mfma_f32_16x16x32_bf16 v[70:73], v[146:149], v[192:195], v[70:73]
	v_mfma_f32_16x16x32_bf16 v[66:69], v[154:157], v[192:195], v[66:69]
	v_mfma_f32_16x16x32_bf16 v[118:121], v[150:153], v[172:175], v[118:121]
	v_mfma_f32_16x16x32_bf16 v[114:117], v[164:167], v[172:175], v[114:117]
	v_mfma_f32_16x16x32_bf16 v[102:105], v[150:153], v[180:183], v[102:105]
	v_mfma_f32_16x16x32_bf16 v[98:101], v[164:167], v[180:183], v[98:101]
	v_mfma_f32_16x16x32_bf16 v[86:89], v[150:153], v[188:191], v[86:89]
	v_mfma_f32_16x16x32_bf16 v[82:85], v[164:167], v[188:191], v[82:85]
	v_mfma_f32_16x16x32_bf16 v[70:73], v[150:153], v[200:203], v[70:73]
	v_mfma_f32_16x16x32_bf16 v[66:69], v[164:167], v[200:203], v[66:69]
	s_barrier
	s_setprio 0
	s_mov_b32 m0, s39
	s_or_b32 s64, s62, 0x80
	ds_read_b128 v[168:171], v162 offset:49152
	ds_read_b128 v[172:175], v162 offset:50176
	ds_read_b128 v[176:179], v162 offset:51200
	ds_read_b128 v[180:183], v162 offset:52224
	ds_read_b128 v[184:187], v162 offset:53248
	ds_read_b128 v[188:191], v162 offset:54272
	ds_read_b128 v[192:195], v162 offset:55296
	ds_read_b128 v[200:203], v162 offset:56320
	buffer_load_dwordx4 v158, s[16:19], s64 offen lds
	s_mov_b32 m0, s40
	s_add_i32 s62, s62, 0xb0080
	buffer_load_dwordx4 v160, s[16:19], s64 offen lds
	s_mov_b32 m0, s43
	s_nop 0
	buffer_load_dwordx4 v158, s[16:19], s62 offen lds
	s_mov_b32 m0, s42
	s_nop 0
	buffer_load_dwordx4 v160, s[16:19], s62 offen lds
	s_add_i32 s61, s61, 2
	s_addk_i32 s2, 0x100
	s_addk_i32 s3, 0x100
	s_cmp_gt_u32 s61, 41
	s_waitcnt vmcnt(6)
	s_waitcnt lgkmcnt(0)
	s_cbranch_scc0 .LBB0_1572
	s_setprio 1
	s_barrier
	v_mfma_f32_16x16x32_bf16 v[62:65], v[130:133], v[168:171], v[62:65]
	v_mfma_f32_16x16x32_bf16 v[58:61], v[138:141], v[168:171], v[58:61]
	v_mfma_f32_16x16x32_bf16 v[46:49], v[130:133], v[176:179], v[46:49]
	v_mfma_f32_16x16x32_bf16 v[42:45], v[138:141], v[176:179], v[42:45]
	v_mfma_f32_16x16x32_bf16 v[30:33], v[130:133], v[184:187], v[30:33]
	v_mfma_f32_16x16x32_bf16 v[26:29], v[138:141], v[184:187], v[26:29]
	v_mfma_f32_16x16x32_bf16 v[14:17], v[130:133], v[192:195], v[14:17]
	v_mfma_f32_16x16x32_bf16 v[10:13], v[138:141], v[192:195], v[10:13]
	v_mfma_f32_16x16x32_bf16 v[62:65], v[134:137], v[172:175], v[62:65]
	v_mfma_f32_16x16x32_bf16 v[58:61], v[142:145], v[172:175], v[58:61]
	v_mfma_f32_16x16x32_bf16 v[46:49], v[134:137], v[180:183], v[46:49]
	v_mfma_f32_16x16x32_bf16 v[42:45], v[142:145], v[180:183], v[42:45]
	v_mfma_f32_16x16x32_bf16 v[30:33], v[134:137], v[188:191], v[30:33]
	v_mfma_f32_16x16x32_bf16 v[26:29], v[142:145], v[188:191], v[26:29]
	v_mfma_f32_16x16x32_bf16 v[14:17], v[134:137], v[200:203], v[14:17]
	v_mfma_f32_16x16x32_bf16 v[10:13], v[142:145], v[200:203], v[10:13]
	v_mfma_f32_16x16x32_bf16 v[54:57], v[146:149], v[168:171], v[54:57]
	v_mfma_f32_16x16x32_bf16 v[50:53], v[154:157], v[168:171], v[50:53]
	v_mfma_f32_16x16x32_bf16 v[38:41], v[146:149], v[176:179], v[38:41]
	v_mfma_f32_16x16x32_bf16 v[34:37], v[154:157], v[176:179], v[34:37]
	v_mfma_f32_16x16x32_bf16 v[22:25], v[146:149], v[184:187], v[22:25]
	v_mfma_f32_16x16x32_bf16 v[18:21], v[154:157], v[184:187], v[18:21]
	v_mfma_f32_16x16x32_bf16 v[6:9], v[146:149], v[192:195], v[6:9]
	v_mfma_f32_16x16x32_bf16 v[2:5], v[154:157], v[192:195], v[2:5]
	v_mfma_f32_16x16x32_bf16 v[54:57], v[150:153], v[172:175], v[54:57]
	v_mfma_f32_16x16x32_bf16 v[50:53], v[164:167], v[172:175], v[50:53]
	v_mfma_f32_16x16x32_bf16 v[38:41], v[150:153], v[180:183], v[38:41]
	v_mfma_f32_16x16x32_bf16 v[34:37], v[164:167], v[180:183], v[34:37]
	v_mfma_f32_16x16x32_bf16 v[22:25], v[150:153], v[188:191], v[22:25]
	v_mfma_f32_16x16x32_bf16 v[18:21], v[164:167], v[188:191], v[18:21]
	v_mfma_f32_16x16x32_bf16 v[6:9], v[150:153], v[200:203], v[6:9]
	v_mfma_f32_16x16x32_bf16 v[2:5], v[164:167], v[200:203], v[2:5]
	s_barrier
	s_setprio 0
	s_mov_b32 m0, s41
	s_nop 0
	buffer_load_dwordx4 v0, s[20:23], s63 offen lds
	s_mov_b32 m0, s33
	s_nop 0
	buffer_load_dwordx4 v159, s[20:23], s63 offen lds
	v_readlane_b32 s2, v251, 45
	v_readlane_b32 s3, v251, 46
	s_and_b64 vcc, exec, s[2:3]
	s_cbranch_vccz .LBB0_1575
	s_barrier

; template <class Epi, bool ALIGN_EPI, bool SP2, class Hook>
; __device__ __forceinline__ void gemm_phase(LAS unsigned char* lds, const Gemm g, const StaticOrder& S, const Epi& E, Acc& acc, const bool fresh, const Hook& H, const int wave_id) {
;     ...
;         if (reset) {
; #pragma unroll
;             for (int a = 0; a < 2; ++a)
; #pragma unroll
;                 for (int b = 0; b < 2; ++b)
; #pragma unroll
;                     for (int m = 0; m < 4; ++m)
; #pragma unroll
;                         for (int n = 0; n < 2; ++n) acc[a][b][m][n] = (f32x4){0.f, 0.f, 0.f, 0.f};
;         }
;         cur = nxt; cA = nA; cB = nB; ++ui;
.LBB0_1613:
	v_mov_b32_e32 v2, 0
	s_add_i32 s2, s13, 0xc0080
	s_add_i32 s3, s12, 0x100
	s_mov_b32 s59, -2
	v_mov_b32_e32 v3, v2
	v_mov_b32_e32 v4, v2
	v_mov_b32_e32 v5, v2
	v_mov_b32_e32 v6, v2
	v_mov_b32_e32 v7, v2
	v_mov_b32_e32 v8, v2
	v_mov_b32_e32 v9, v2
	v_mov_b32_e32 v18, v2
	v_mov_b32_e32 v19, v2
	v_mov_b32_e32 v20, v2
	v_mov_b32_e32 v21, v2
	v_mov_b32_e32 v22, v2
	v_mov_b32_e32 v23, v2
	v_mov_b32_e32 v24, v2
	v_mov_b32_e32 v25, v2
	v_mov_b32_e32 v34, v2
	v_mov_b32_e32 v35, v2
	v_mov_b32_e32 v36, v2
	v_mov_b32_e32 v37, v2
	v_mov_b32_e32 v38, v2
	v_mov_b32_e32 v39, v2
	v_mov_b32_e32 v40, v2
	v_mov_b32_e32 v41, v2
	v_mov_b32_e32 v50, v2
	v_mov_b32_e32 v51, v2
	v_mov_b32_e32 v52, v2
	v_mov_b32_e32 v53, v2
	v_mov_b32_e32 v54, v2
	v_mov_b32_e32 v55, v2
	v_mov_b32_e32 v56, v2
	v_mov_b32_e32 v57, v2
	v_mov_b32_e32 v10, v2
	v_mov_b32_e32 v11, v2
	v_mov_b32_e32 v12, v2
	v_mov_b32_e32 v13, v2
	v_mov_b32_e32 v14, v2
	v_mov_b32_e32 v15, v2
	v_mov_b32_e32 v16, v2
	v_mov_b32_e32 v17, v2
	v_mov_b32_e32 v26, v2
	v_mov_b32_e32 v27, v2
	v_mov_b32_e32 v28, v2
	v_mov_b32_e32 v29, v2
	v_mov_b32_e32 v30, v2
	v_mov_b32_e32 v31, v2
	v_mov_b32_e32 v32, v2
	v_mov_b32_e32 v33, v2
	v_mov_b32_e32 v42, v2
	v_mov_b32_e32 v43, v2
	v_mov_b32_e32 v44, v2
	v_mov_b32_e32 v45, v2
	v_mov_b32_e32 v46, v2
	v_mov_b32_e32 v47, v2
	v_mov_b32_e32 v48, v2
	v_mov_b32_e32 v49, v2
	v_mov_b32_e32 v58, v2
	v_mov_b32_e32 v59, v2
	v_mov_b32_e32 v60, v2
	v_mov_b32_e32 v61, v2
	v_mov_b32_e32 v62, v2
	v_mov_b32_e32 v63, v2
	v_mov_b32_e32 v64, v2
	v_mov_b32_e32 v65, v2
	v_mov_b32_e32 v66, v2
	v_mov_b32_e32 v67, v2
	v_mov_b32_e32 v68, v2
	v_mov_b32_e32 v69, v2
	v_mov_b32_e32 v70, v2
	v_mov_b32_e32 v71, v2
	v_mov_b32_e32 v72, v2
	v_mov_b32_e32 v73, v2
	v_mov_b32_e32 v82, v2
	v_mov_b32_e32 v83, v2
	v_mov_b32_e32 v84, v2
	v_mov_b32_e32 v85, v2
	v_mov_b32_e32 v86, v2
	v_mov_b32_e32 v87, v2
	v_mov_b32_e32 v88, v2
	v_mov_b32_e32 v89, v2
	v_mov_b32_e32 v98, v2
	v_mov_b32_e32 v99, v2
	v_mov_b32_e32 v100, v2
	v_mov_b32_e32 v101, v2
	v_mov_b32_e32 v102, v2
	v_mov_b32_e32 v103, v2
	v_mov_b32_e32 v104, v2
	v_mov_b32_e32 v105, v2
	v_mov_b32_e32 v114, v2
	v_mov_b32_e32 v115, v2
	v_mov_b32_e32 v116, v2
	v_mov_b32_e32 v117, v2
	v_mov_b32_e32 v118, v2
	v_mov_b32_e32 v119, v2
	v_mov_b32_e32 v120, v2
	v_mov_b32_e32 v121, v2
	v_mov_b32_e32 v74, v2
	v_mov_b32_e32 v75, v2
	v_mov_b32_e32 v76, v2
	v_mov_b32_e32 v77, v2
	v_mov_b32_e32 v78, v2
	v_mov_b32_e32 v79, v2
	v_mov_b32_e32 v80, v2
	v_mov_b32_e32 v81, v2
	v_mov_b32_e32 v90, v2
	v_mov_b32_e32 v91, v2
	v_mov_b32_e32 v92, v2
	v_mov_b32_e32 v93, v2
	v_mov_b32_e32 v94, v2
	v_mov_b32_e32 v95, v2
	v_mov_b32_e32 v96, v2
	v_mov_b32_e32 v97, v2
	v_mov_b32_e32 v106, v2
	v_mov_b32_e32 v107, v2
	v_mov_b32_e32 v108, v2
	v_mov_b32_e32 v109, v2
	v_mov_b32_e32 v110, v2
	v_mov_b32_e32 v111, v2
	v_mov_b32_e32 v112, v2
	v_mov_b32_e32 v113, v2
	v_mov_b32_e32 v122, v2
	v_mov_b32_e32 v123, v2
	v_mov_b32_e32 v124, v2
	v_mov_b32_e32 v125, v2
	v_mov_b32_e32 v126, v2
	v_mov_b32_e32 v127, v2
	v_mov_b32_e32 v128, v2
	v_mov_b32_e32 v129, v2
	s_branch .Lrot_in_10
.LBB0_1614:
	s_setprio 1
	s_barrier
	v_mfma_f32_16x16x32_bf16 v[62:65], v[130:133], v[162:165], v[62:65]
	v_mfma_f32_16x16x32_bf16 v[58:61], v[138:141], v[162:165], v[58:61]
	v_mfma_f32_16x16x32_bf16 v[46:49], v[130:133], v[178:181], v[46:49]
	v_mfma_f32_16x16x32_bf16 v[42:45], v[138:141], v[178:181], v[42:45]
	v_mfma_f32_16x16x32_bf16 v[30:33], v[130:133], v[186:189], v[30:33]
	v_mfma_f32_16x16x32_bf16 v[26:29], v[138:141], v[186:189], v[26:29]
	v_mfma_f32_16x16x32_bf16 v[14:17], v[130:133], v[194:197], v[14:17]
	v_mfma_f32_16x16x32_bf16 v[10:13], v[138:141], v[194:197], v[10:13]
	v_mfma_f32_16x16x32_bf16 v[62:65], v[134:137], v[174:177], v[62:65]
	v_mfma_f32_16x16x32_bf16 v[58:61], v[142:145], v[174:177], v[58:61]
	v_mfma_f32_16x16x32_bf16 v[46:49], v[134:137], v[182:185], v[46:49]
	v_mfma_f32_16x16x32_bf16 v[42:45], v[142:145], v[182:185], v[42:45]
	v_mfma_f32_16x16x32_bf16 v[30:33], v[134:137], v[190:193], v[30:33]
	v_mfma_f32_16x16x32_bf16 v[26:29], v[142:145], v[190:193], v[26:29]
	v_mfma_f32_16x16x32_bf16 v[14:17], v[134:137], v[200:203], v[14:17]
	v_mfma_f32_16x16x32_bf16 v[10:13], v[142:145], v[200:203], v[10:13]
	v_mfma_f32_16x16x32_bf16 v[54:57], v[146:149], v[162:165], v[54:57]
	v_mfma_f32_16x16x32_bf16 v[50:53], v[154:157], v[162:165], v[50:53]
	v_mfma_f32_16x16x32_bf16 v[38:41], v[146:149], v[178:181], v[38:41]
	v_mfma_f32_16x16x32_bf16 v[34:37], v[154:157], v[178:181], v[34:37]
	v_mfma_f32_16x16x32_bf16 v[22:25], v[146:149], v[186:189], v[22:25]
	v_mfma_f32_16x16x32_bf16 v[18:21], v[154:157], v[186:189], v[18:21]
	v_mfma_f32_16x16x32_bf16 v[6:9], v[146:149], v[194:197], v[6:9]
	v_mfma_f32_16x16x32_bf16 v[2:5], v[154:157], v[194:197], v[2:5]
	v_mfma_f32_16x16x32_bf16 v[54:57], v[150:153], v[174:177], v[54:57]
	v_mfma_f32_16x16x32_bf16 v[50:53], v[158:161], v[174:177], v[50:53]
	v_mfma_f32_16x16x32_bf16 v[38:41], v[150:153], v[182:185], v[38:41]
	v_mfma_f32_16x16x32_bf16 v[34:37], v[158:161], v[182:185], v[34:37]
	v_mfma_f32_16x16x32_bf16 v[22:25], v[150:153], v[190:193], v[22:25]
	v_mfma_f32_16x16x32_bf16 v[18:21], v[158:161], v[190:193], v[18:21]
	v_mfma_f32_16x16x32_bf16 v[6:9], v[150:153], v[200:203], v[6:9]
	v_mfma_f32_16x16x32_bf16 v[2:5], v[158:161], v[200:203], v[2:5]
	s_barrier
	s_setprio 0
; template <class Epi, bool ALIGN_EPI, bool SP2, class Hook>
; __device__ __forceinline__ void gemm_phase(LAS unsigned char* lds, const Gemm g, const StaticOrder& S, const Epi& E, Acc& acc, const bool fresh, const Hook& H, const int wave_id) {
;     ...
;             const Src a1 = cA + (size_t)(t + 1) * kstep;
;             const Src a2 = last ? nA : cA + (size_t)(t + 2) * kstep, b2 = last ? nB : cB + (size_t)(t + 2) * kstep;
;             const Src a3 = a2 + kstep, b3 = b2 + kstep;
.Lrot_in_10:
	s_add_i32 s100, s2, 0xfff40000
	v_add_u32_e32 v0, 0x10000, v172
	ds_read_b128 v[130:133], v0
	ds_read_b128 v[134:137], v0 offset:1024
	ds_read_b128 v[138:141], v0 offset:2048
	ds_read_b128 v[142:145], v0 offset:3072
	v_add_u32_e32 v0, 0x14000, v172
	ds_read_b128 v[146:149], v0
	ds_read_b128 v[150:153], v0 offset:1024
	ds_read_b128 v[154:157], v0 offset:2048
	ds_read_b128 v[158:161], v0 offset:3072
	s_mov_b32 m0, s41
	s_nop 0
	buffer_load_dwordx4 v168, s[8:11], s100 offen lds
	s_mov_b32 m0, s33
	s_nop 0
	buffer_load_dwordx4 v170, s[8:11], s100 offen lds
	s_mov_b32 m0, s45
	ds_read_b128 v[162:165], v173
	ds_read_b128 v[174:177], v173 offset:1024
	ds_read_b128 v[178:181], v173 offset:2048
	ds_read_b128 v[182:185], v173 offset:3072
	ds_read_b128 v[186:189], v173 offset:4096
	ds_read_b128 v[190:193], v173 offset:5120
	ds_read_b128 v[194:197], v173 offset:6144
	ds_read_b128 v[200:203], v173 offset:7168
	buffer_load_dwordx4 v168, s[8:11], s2 offen lds
	s_mov_b32 m0, s46
	s_nop 0
	buffer_load_dwordx4 v170, s[8:11], s2 offen lds
	s_waitcnt vmcnt(8)
	s_waitcnt lgkmcnt(0)
	s_setprio 1
	s_barrier
	v_mfma_f32_16x16x32_bf16 v[126:129], v[130:133], v[162:165], v[126:129]
	v_mfma_f32_16x16x32_bf16 v[122:125], v[138:141], v[162:165], v[122:125]
	v_mfma_f32_16x16x32_bf16 v[110:113], v[130:133], v[178:181], v[110:113]
	v_mfma_f32_16x16x32_bf16 v[106:109], v[138:141], v[178:181], v[106:109]
	v_mfma_f32_16x16x32_bf16 v[94:97], v[130:133], v[186:189], v[94:97]
	v_mfma_f32_16x16x32_bf16 v[90:93], v[138:141], v[186:189], v[90:93]
	v_mfma_f32_16x16x32_bf16 v[78:81], v[130:133], v[194:197], v[78:81]
	v_mfma_f32_16x16x32_bf16 v[74:77], v[138:141], v[194:197], v[74:77]
	v_mfma_f32_16x16x32_bf16 v[126:129], v[134:137], v[174:177], v[126:129]
	v_mfma_f32_16x16x32_bf16 v[122:125], v[142:145], v[174:177], v[122:125]
	v_mfma_f32_16x16x32_bf16 v[110:113], v[134:137], v[182:185], v[110:113]
	v_mfma_f32_16x16x32_bf16 v[106:109], v[142:145], v[182:185], v[106:109]
	v_mfma_f32_16x16x32_bf16 v[94:97], v[134:137], v[190:193], v[94:97]
	v_mfma_f32_16x16x32_bf16 v[90:93], v[142:145], v[190:193], v[90:93]
	v_mfma_f32_16x16x32_bf16 v[78:81], v[134:137], v[200:203], v[78:81]
	v_mfma_f32_16x16x32_bf16 v[74:77], v[142:145], v[200:203], v[74:77]
	v_mfma_f32_16x16x32_bf16 v[118:121], v[146:149], v[162:165], v[118:121]
	v_mfma_f32_16x16x32_bf16 v[114:117], v[154:157], v[162:165], v[114:117]
	v_mfma_f32_16x16x32_bf16 v[102:105], v[146:149], v[178:181], v[102:105]
	v_mfma_f32_16x16x32_bf16 v[98:101], v[154:157], v[178:181], v[98:101]
	v_mfma_f32_16x16x32_bf16 v[86:89], v[146:149], v[186:189], v[86:89]
	v_mfma_f32_16x16x32_bf16 v[82:85], v[154:157], v[186:189], v[82:85]
	v_mfma_f32_16x16x32_bf16 v[70:73], v[146:149], v[194:197], v[70:73]
	v_mfma_f32_16x16x32_bf16 v[66:69], v[154:157], v[194:197], v[66:69]
	v_mfma_f32_16x16x32_bf16 v[118:121], v[150:153], v[174:177], v[118:121]
	v_mfma_f32_16x16x32_bf16 v[114:117], v[158:161], v[174:177], v[114:117]
	v_mfma_f32_16x16x32_bf16 v[102:105], v[150:153], v[182:185], v[102:105]
	v_mfma_f32_16x16x32_bf16 v[98:101], v[158:161], v[182:185], v[98:101]
	v_mfma_f32_16x16x32_bf16 v[86:89], v[150:153], v[190:193], v[86:89]
	v_mfma_f32_16x16x32_bf16 v[82:85], v[158:161], v[190:193], v[82:85]
	v_mfma_f32_16x16x32_bf16 v[70:73], v[150:153], v[200:203], v[70:73]
	v_mfma_f32_16x16x32_bf16 v[66:69], v[158:161], v[200:203], v[66:69]
	s_barrier
	s_setprio 0
	s_add_i32 s12, s2, 0xfff40080
	s_cmp_eq_u32 s59, 40
	s_cselect_b32 s62, s55, s12
	s_cselect_b32 s13, s31, s77
	s_cselect_b32 s12, s30, s76
	s_cselect_b32 s15, s35, s51
	s_cselect_b32 s14, s34, s50
	s_cselect_b32 s60, s56, s3
	s_cselect_b32 s16, s20, s8
	s_cselect_b32 s17, s21, s9
	s_cselect_b32 s18, s22, s10
	s_cselect_b32 s19, s23, s11
	s_or_b32 s61, s62, 0x80
	s_mov_b32 m0, s92
	ds_read_b128 v[162:165], v173 offset:16384
	ds_read_b128 v[174:177], v173 offset:17408
	ds_read_b128 v[178:181], v173 offset:18432
	ds_read_b128 v[182:185], v173 offset:19456
	ds_read_b128 v[186:189], v173 offset:20480
	ds_read_b128 v[190:193], v173 offset:21504
	ds_read_b128 v[194:197], v173 offset:22528
	ds_read_b128 v[200:203], v173 offset:23552
	buffer_load_dwordx4 v169, s[12:15], s60 offen lds
	s_mov_b32 m0, s93
	s_add_i32 s63, s60, 0xb0000
	buffer_load_dwordx4 v171, s[12:15], s60 offen lds
	s_mov_b32 m0, s94
	s_nop 0
	buffer_load_dwordx4 v169, s[12:15], s63 offen lds
	s_mov_b32 m0, s95
	s_nop 0
	buffer_load_dwordx4 v171, s[12:15], s63 offen lds
	s_waitcnt vmcnt(6)
	s_waitcnt lgkmcnt(0)
	s_setprio 1
	s_barrier
	v_mfma_f32_16x16x32_bf16 v[62:65], v[130:133], v[162:165], v[62:65]
	v_mfma_f32_16x16x32_bf16 v[58:61], v[138:141], v[162:165], v[58:61]
	v_mfma_f32_16x16x32_bf16 v[46:49], v[130:133], v[178:181], v[46:49]
	v_mfma_f32_16x16x32_bf16 v[42:45], v[138:141], v[178:181], v[42:45]
	v_mfma_f32_16x16x32_bf16 v[30:33], v[130:133], v[186:189], v[30:33]
	v_mfma_f32_16x16x32_bf16 v[26:29], v[138:141], v[186:189], v[26:29]
	v_mfma_f32_16x16x32_bf16 v[14:17], v[130:133], v[194:197], v[14:17]
	v_mfma_f32_16x16x32_bf16 v[10:13], v[138:141], v[194:197], v[10:13]
	v_mfma_f32_16x16x32_bf16 v[62:65], v[134:137], v[174:177], v[62:65]
	v_mfma_f32_16x16x32_bf16 v[58:61], v[142:145], v[174:177], v[58:61]
	v_mfma_f32_16x16x32_bf16 v[46:49], v[134:137], v[182:185], v[46:49]
	v_mfma_f32_16x16x32_bf16 v[42:45], v[142:145], v[182:185], v[42:45]
	v_mfma_f32_16x16x32_bf16 v[30:33], v[134:137], v[190:193], v[30:33]
	v_mfma_f32_16x16x32_bf16 v[26:29], v[142:145], v[190:193], v[26:29]
	v_mfma_f32_16x16x32_bf16 v[14:17], v[134:137], v[200:203], v[14:17]
	v_mfma_f32_16x16x32_bf16 v[10:13], v[142:145], v[200:203], v[10:13]
	v_mfma_f32_16x16x32_bf16 v[54:57], v[146:149], v[162:165], v[54:57]
	v_mfma_f32_16x16x32_bf16 v[50:53], v[154:157], v[162:165], v[50:53]
	v_mfma_f32_16x16x32_bf16 v[38:41], v[146:149], v[178:181], v[38:41]
	v_mfma_f32_16x16x32_bf16 v[34:37], v[154:157], v[178:181], v[34:37]
	v_mfma_f32_16x16x32_bf16 v[22:25], v[146:149], v[186:189], v[22:25]
	v_mfma_f32_16x16x32_bf16 v[18:21], v[154:157], v[186:189], v[18:21]
	v_mfma_f32_16x16x32_bf16 v[6:9], v[146:149], v[194:197], v[6:9]
	v_mfma_f32_16x16x32_bf16 v[2:5], v[154:157], v[194:197], v[2:5]
	v_mfma_f32_16x16x32_bf16 v[54:57], v[150:153], v[174:177], v[54:57]
	v_mfma_f32_16x16x32_bf16 v[50:53], v[158:161], v[174:177], v[50:53]
	v_mfma_f32_16x16x32_bf16 v[38:41], v[150:153], v[182:185], v[38:41]
	v_mfma_f32_16x16x32_bf16 v[34:37], v[158:161], v[182:185], v[34:37]
	v_mfma_f32_16x16x32_bf16 v[22:25], v[150:153], v[190:193], v[22:25]
	v_mfma_f32_16x16x32_bf16 v[18:21], v[158:161], v[190:193], v[18:21]
	v_mfma_f32_16x16x32_bf16 v[6:9], v[150:153], v[200:203], v[6:9]
	v_mfma_f32_16x16x32_bf16 v[2:5], v[158:161], v[200:203], v[2:5]
	s_barrier
; template <class Epi, bool ALIGN_EPI, bool SP2, class Hook>
; __device__ __forceinline__ void gemm_phase(LAS unsigned char* lds, const Gemm g, const StaticOrder& S, const Epi& E, Acc& acc, const bool fresh, const Hook& H, const int wave_id) {
;     ...
;         for (int t = t0; t < nt; t += 2) {
;             const bool last = (t == nt - 2);
	s_setprio 0
	s_mov_b32 m0, s44
	s_nop 0
	buffer_load_dwordx4 v168, s[16:19], s62 offen lds
	s_mov_b32 m0, s36
	s_nop 0
	buffer_load_dwordx4 v170, s[16:19], s62 offen lds
	v_add_u32_e32 v0, 0x18000, v172
	ds_read_b128 v[130:133], v0
	ds_read_b128 v[134:137], v0 offset:1024
	ds_read_b128 v[138:141], v0 offset:2048
	ds_read_b128 v[142:145], v0 offset:3072
	v_add_u32_e32 v0, 0x1c000, v172
	ds_read_b128 v[146:149], v0
	ds_read_b128 v[150:153], v0 offset:1024
	ds_read_b128 v[154:157], v0 offset:2048
	ds_read_b128 v[158:161], v0 offset:3072
	s_add_i32 s62, s62, 0xc0000
	s_mov_b32 m0, s37
	ds_read_b128 v[162:165], v173 offset:32768
	ds_read_b128 v[174:177], v173 offset:33792
	ds_read_b128 v[178:181], v173 offset:34816
	ds_read_b128 v[182:185], v173 offset:35840
	ds_read_b128 v[186:189], v173 offset:36864
	ds_read_b128 v[190:193], v173 offset:37888
	ds_read_b128 v[194:197], v173 offset:38912
	ds_read_b128 v[200:203], v173 offset:39936
	buffer_load_dwordx4 v168, s[16:19], s62 offen lds
	s_mov_b32 m0, s38
	s_nop 0
	buffer_load_dwordx4 v170, s[16:19], s62 offen lds
	s_waitcnt vmcnt(8)
	s_waitcnt lgkmcnt(0)
	s_setprio 1
	s_barrier
	v_mfma_f32_16x16x32_bf16 v[126:129], v[130:133], v[162:165], v[126:129]
	v_mfma_f32_16x16x32_bf16 v[122:125], v[138:141], v[162:165], v[122:125]
	v_mfma_f32_16x16x32_bf16 v[110:113], v[130:133], v[178:181], v[110:113]
	v_mfma_f32_16x16x32_bf16 v[106:109], v[138:141], v[178:181], v[106:109]
	v_mfma_f32_16x16x32_bf16 v[94:97], v[130:133], v[186:189], v[94:97]
	v_mfma_f32_16x16x32_bf16 v[90:93], v[138:141], v[186:189], v[90:93]
	v_mfma_f32_16x16x32_bf16 v[78:81], v[130:133], v[194:197], v[78:81]
	v_mfma_f32_16x16x32_bf16 v[74:77], v[138:141], v[194:197], v[74:77]
	v_mfma_f32_16x16x32_bf16 v[126:129], v[134:137], v[174:177], v[126:129]
	v_mfma_f32_16x16x32_bf16 v[122:125], v[142:145], v[174:177], v[122:125]
	v_mfma_f32_16x16x32_bf16 v[110:113], v[134:137], v[182:185], v[110:113]
	v_mfma_f32_16x16x32_bf16 v[106:109], v[142:145], v[182:185], v[106:109]
	v_mfma_f32_16x16x32_bf16 v[94:97], v[134:137], v[190:193], v[94:97]
	v_mfma_f32_16x16x32_bf16 v[90:93], v[142:145], v[190:193], v[90:93]
	v_mfma_f32_16x16x32_bf16 v[78:81], v[134:137], v[200:203], v[78:81]
	v_mfma_f32_16x16x32_bf16 v[74:77], v[142:145], v[200:203], v[74:77]
	v_mfma_f32_16x16x32_bf16 v[118:121], v[146:149], v[162:165], v[118:121]
	v_mfma_f32_16x16x32_bf16 v[114:117], v[154:157], v[162:165], v[114:117]
	v_mfma_f32_16x16x32_bf16 v[102:105], v[146:149], v[178:181], v[102:105]
	v_mfma_f32_16x16x32_bf16 v[98:101], v[154:157], v[178:181], v[98:101]
	v_mfma_f32_16x16x32_bf16 v[86:89], v[146:149], v[186:189], v[86:89]
	v_mfma_f32_16x16x32_bf16 v[82:85], v[154:157], v[186:189], v[82:85]
	v_mfma_f32_16x16x32_bf16 v[70:73], v[146:149], v[194:197], v[70:73]
	v_mfma_f32_16x16x32_bf16 v[66:69], v[154:157], v[194:197], v[66:69]
	v_mfma_f32_16x16x32_bf16 v[118:121], v[150:153], v[174:177], v[118:121]
	v_mfma_f32_16x16x32_bf16 v[114:117], v[158:161], v[174:177], v[114:117]
	v_mfma_f32_16x16x32_bf16 v[102:105], v[150:153], v[182:185], v[102:105]
	v_mfma_f32_16x16x32_bf16 v[98:101], v[158:161], v[182:185], v[98:101]
	v_mfma_f32_16x16x32_bf16 v[86:89], v[150:153], v[190:193], v[86:89]
	v_mfma_f32_16x16x32_bf16 v[82:85], v[158:161], v[190:193], v[82:85]
	v_mfma_f32_16x16x32_bf16 v[70:73], v[150:153], v[200:203], v[70:73]
	v_mfma_f32_16x16x32_bf16 v[66:69], v[158:161], v[200:203], v[66:69]
	s_barrier
	s_setprio 0
	s_mov_b32 m0, s39
	s_or_b32 s62, s60, 0x80
	ds_read_b128 v[162:165], v173 offset:49152
	ds_read_b128 v[174:177], v173 offset:50176
	ds_read_b128 v[178:181], v173 offset:51200
	ds_read_b128 v[182:185], v173 offset:52224
	ds_read_b128 v[186:189], v173 offset:53248
	ds_read_b128 v[190:193], v173 offset:54272
	ds_read_b128 v[194:197], v173 offset:55296
	ds_read_b128 v[200:203], v173 offset:56320
	buffer_load_dwordx4 v169, s[12:15], s62 offen lds
	s_mov_b32 m0, s40
	s_add_i32 s60, s60, 0xb0080
	buffer_load_dwordx4 v171, s[12:15], s62 offen lds
	s_mov_b32 m0, s43
	s_nop 0
	buffer_load_dwordx4 v169, s[12:15], s60 offen lds
	s_mov_b32 m0, s42
	s_nop 0
	buffer_load_dwordx4 v171, s[12:15], s60 offen lds
	s_add_i32 s59, s59, 2
	s_addk_i32 s2, 0x100
	s_addk_i32 s3, 0x100
	s_cmp_gt_u32 s59, 41
	s_waitcnt vmcnt(6)
	s_waitcnt lgkmcnt(0)
	s_cbranch_scc0 .LBB0_1614
	s_setprio 1
	s_barrier
	v_mfma_f32_16x16x32_bf16 v[62:65], v[130:133], v[162:165], v[62:65]
	v_mfma_f32_16x16x32_bf16 v[58:61], v[138:141], v[162:165], v[58:61]
	v_mfma_f32_16x16x32_bf16 v[46:49], v[130:133], v[178:181], v[46:49]
	v_mfma_f32_16x16x32_bf16 v[42:45], v[138:141], v[178:181], v[42:45]
	v_mfma_f32_16x16x32_bf16 v[30:33], v[130:133], v[186:189], v[30:33]
	v_mfma_f32_16x16x32_bf16 v[26:29], v[138:141], v[186:189], v[26:29]
	v_mfma_f32_16x16x32_bf16 v[14:17], v[130:133], v[194:197], v[14:17]
	v_mfma_f32_16x16x32_bf16 v[10:13], v[138:141], v[194:197], v[10:13]
	v_mfma_f32_16x16x32_bf16 v[62:65], v[134:137], v[174:177], v[62:65]
	v_mfma_f32_16x16x32_bf16 v[58:61], v[142:145], v[174:177], v[58:61]
	v_mfma_f32_16x16x32_bf16 v[46:49], v[134:137], v[182:185], v[46:49]
	v_mfma_f32_16x16x32_bf16 v[42:45], v[142:145], v[182:185], v[42:45]
	v_mfma_f32_16x16x32_bf16 v[30:33], v[134:137], v[190:193], v[30:33]
	v_mfma_f32_16x16x32_bf16 v[26:29], v[142:145], v[190:193], v[26:29]
	v_mfma_f32_16x16x32_bf16 v[14:17], v[134:137], v[200:203], v[14:17]
	v_mfma_f32_16x16x32_bf16 v[10:13], v[142:145], v[200:203], v[10:13]
	v_mfma_f32_16x16x32_bf16 v[54:57], v[146:149], v[162:165], v[54:57]
	v_mfma_f32_16x16x32_bf16 v[50:53], v[154:157], v[162:165], v[50:53]
	v_mfma_f32_16x16x32_bf16 v[38:41], v[146:149], v[178:181], v[38:41]
	v_mfma_f32_16x16x32_bf16 v[34:37], v[154:157], v[178:181], v[34:37]
	v_mfma_f32_16x16x32_bf16 v[22:25], v[146:149], v[186:189], v[22:25]
	v_mfma_f32_16x16x32_bf16 v[18:21], v[154:157], v[186:189], v[18:21]
	v_mfma_f32_16x16x32_bf16 v[6:9], v[146:149], v[194:197], v[6:9]
	v_mfma_f32_16x16x32_bf16 v[2:5], v[154:157], v[194:197], v[2:5]
	v_mfma_f32_16x16x32_bf16 v[54:57], v[150:153], v[174:177], v[54:57]
	v_mfma_f32_16x16x32_bf16 v[50:53], v[158:161], v[174:177], v[50:53]
	v_mfma_f32_16x16x32_bf16 v[38:41], v[150:153], v[182:185], v[38:41]
	v_mfma_f32_16x16x32_bf16 v[34:37], v[158:161], v[182:185], v[34:37]
	v_mfma_f32_16x16x32_bf16 v[22:25], v[150:153], v[190:193], v[22:25]
	v_mfma_f32_16x16x32_bf16 v[18:21], v[158:161], v[190:193], v[18:21]
	v_mfma_f32_16x16x32_bf16 v[6:9], v[150:153], v[200:203], v[6:9]
	v_mfma_f32_16x16x32_bf16 v[2:5], v[158:161], v[200:203], v[2:5]
	s_barrier
	s_setprio 0
	s_mov_b32 m0, s41
	s_nop 0
	buffer_load_dwordx4 v168, s[16:19], s61 offen lds
	s_mov_b32 m0, s33
	s_nop 0
	buffer_load_dwordx4 v170, s[16:19], s61 offen lds
	v_readlane_b32 s2, v251, 45
	v_readlane_b32 s3, v251, 46
	s_and_b64 vcc, exec, s[2:3]
	s_cbranch_vccz .LBB0_1617
	s_barrier
